# v066 + the leading half's epilogue-alignment barrier sits below the epilogue's address set-up and first loads (GLU 14, PR0 8, WO/FD 4 loads in flight during the wait)
# speedup vs baseline: 1.0084x; 1.0049x over previous
;     __device__ __forceinline__ void operator()(const f32x4 (&acc)[2][2][4][2], const Unit& u, int wr, int wc, int fr_in, int fq_in) const {
;         int fr = fr_in, fq = fq_in; asm volatile("" : "+v"(fr), "+v"(fq));
;         const int row0 = u.pm * BM + wr * 64 + fr;
;         if (u.pn >= 4 && u.pn <= 8) {
;     ...
;         const int col0 = u.pn * BM + wc * 32 + 8 * fq;
;         const bool isg = u.pn >= 10, isv = u.pn == 9;
;         bf16_t* const pbase = P + (size_t)row0 * NPJ + col0;
;         f32x4 bv[2][2];
; #pragma unroll
;         for (int bj = 0; bj < 2; ++bj)
; #pragma unroll
;             for (int n = 0; n < 2; ++n) bv[bj][n] = isg ? *(const f32x4*)(bgate + (col0 - 2560) + bj * HALF + 4 * n) : (f32x4){0.f, 0.f, 0.f, 0.f};
.Lpx_270:
	s_lshl_b32 s0, s78, 8
	v_mov_b32_e32 v223, v99
	v_mov_b32_e32 v224, v1
	s_add_i32 s0, s0, s6
	v_readlane_b32 s60, v251, 14
	v_add_u32_e32 v192, s0, v224
	s_add_i32 s0, s95, -4
	s_and_b64 vcc, exec, s[10:11]
	s_cbranch_vccz .LBB0_273
	s_barrier
.LBB0_273:
	s_cmp_gt_u32 s0, 4
	s_mov_b64 s[38:39], -1
	v_readlane_b32 s61, v251, 15
	v_readlane_b32 s62, v251, 16
	v_readlane_b32 s63, v251, 17
	v_readlane_b32 s64, v251, 18
	v_readlane_b32 s65, v251, 19
	v_readlane_b32 s66, v251, 20
	v_readlane_b32 s67, v251, 21
	s_cbranch_scc0 .LBB0_443
	s_lshl_b32 s0, s95, 8
	v_readlane_b32 s1, v255, 0
	s_or_b32 s0, s0, s1
	s_cmp_gt_i32 s95, 9
	v_lshl_add_u32 v152, v223, 3, s0
	s_cselect_b64 s[42:43], -1, 0
	s_cmp_lt_i32 s95, 10
	v_readlane_b32 s0, v254, 60
	s_cselect_b64 s[40:41], -1, 0
	v_ashrrev_i32_e32 v153, 31, v152
	v_readlane_b32 s1, v254, 61
	v_mov_b32_e32 v140, 0
	s_and_b64 vcc, exec, s[40:41]
	v_lshl_add_u64 v[148:149], v[152:153], 2, s[0:1]
	v_mov_b32_e32 v144, 0
	v_mov_b32_e32 v145, 0
	v_mov_b32_e32 v146, 0
	v_mov_b32_e32 v147, 0
	s_cbranch_vccnz .LBB0_276
	v_add_co_u32_e32 v132, vcc, 0xffffe000, v148
	s_nop 1
	v_addc_co_u32_e32 v133, vcc, -1, v149, vcc
	global_load_dwordx4 v[144:147], v[132:133], off offset:-2048

; #define GAS __attribute__((address_space(1)))
; __device__ __forceinline__ u32x4 pack8(f32x4 v0, f32x4 v1) { u32x4 w; w.x = cvt_pk_bf16(v0[0], v0[1]); w.y = cvt_pk_bf16(v0[2], v0[3]); w.z = cvt_pk_bf16(v1[0], v1[1]); w.w = cvt_pk_bf16(v1[2], v1[3]); return w; }
; __device__ __forceinline__ void unpack8(u32x4 w, f32x4& v0, f32x4& v1) { v0 = (f32x4){bflo(w.x), bfhi(w.x), bflo(w.y), bfhi(w.y)}; v1 = (f32x4){bflo(w.z), bfhi(w.z), bflo(w.w), bfhi(w.w)}; }
; #define PG8_BAR __builtin_amdgcn_s_barrier()
; #define GAS __attribute__((address_space(1)))
;     __device__ __forceinline__ void operator()(const f32x4 (&acc)[2][2][4][2], const Unit& u, int wr, int wc, int fr, int fq) const {
;         const int row0 = u.pm * BM + wr * 64 + fr, col0 = u.pn * BM + wc * 32 + 8 * fq;
;         f32x4 bv[2][2];
; #pragma unroll
;         for (int bj = 0; bj < 2; ++bj)
; #pragma unroll
;             for (int n = 0; n < 2; ++n) bv[bj][n] = *(const f32x4*)(bglu + col0 + bj * HALF + 4 * n);
;         const bf16_t* const zb = Z + (size_t)row0 * 1024 + col0; bf16_t* const sob = SO + (size_t)row0 * 1024 + col0;
; #pragma unroll
;         for (int ai = 0; ai < 2; ++ai)
; #pragma unroll
;             for (int m = 0; m < 4; ++m) { const size_t off = (size_t)(ai * HALF + m * 16) * 1024;
; #pragma unroll
;                 for (int bj = 0; bj < 2; ++bj) { f32x4 z0, z1; unpack8(*(const GAS u32x4*)(zb + off + bj * HALF), z0, z1);
;                     const f32x4 v0 = z0 * sigmoid4(acc[ai][bj][m][0] + bv[bj][0]), v1 = z1 * sigmoid4(acc[ai][bj][m][1] + bv[bj][1]);
;                     *(GAS u32x4*)(sob + off + bj * HALF) = pack8(v0, v1); } }
; template <class Epi, class Sched, bool ALIGN_EPI = false, bool SP2 = false>
; __device__ __forceinline__ void gemm_phase(PG8_LAS unsigned char* lds, const Gemm g, const Sched& S, const Epi& E) {
;     ...
;         if constexpr (ALIGN_EPI) { if (wr == 0) PG8_BAR; }
.Lpx_936:
	v_lshl_or_b32 v160, s24, 8, v164
	v_ashrrev_i32_e32 v161, 31, v160
	v_lshl_add_u64 v[22:23], v[160:161], 2, s[8:9]
	global_load_dwordx4 v[34:37], v[22:23], off offset:16
	global_load_dwordx4 v[38:41], v[22:23], off
	global_load_dwordx4 v[14:17], v[22:23], off offset:528
	s_nop 0
	global_load_dwordx4 v[22:25], v[22:23], off offset:512
	v_lshl_add_u32 v162, s42, 8, v1
	v_ashrrev_i32_e32 v163, 31, v162
	v_lshlrev_b64 v[166:167], 11, v[162:163]
	v_lshl_add_u64 v[162:163], s[4:5], 0, v[166:167]
	v_lshlrev_b64 v[160:161], 1, v[160:161]
	v_lshl_add_u64 v[162:163], v[162:163], 0, v[160:161]
	global_load_dwordx4 v[184:187], v[162:163], off
	global_load_dwordx4 v[188:191], v[162:163], off offset:256
	v_add_co_u32_e32 v242, vcc, s94, v162
	v_addc_co_u32_e32 v243, vcc, 0, v163, vcc
	global_load_dwordx4 v[192:195], v[242:243], off
	global_load_dwordx4 v[196:199], v[242:243], off offset:256
	v_add_co_u32_e32 v242, vcc, s73, v162
	v_addc_co_u32_e32 v243, vcc, 0, v163, vcc
	global_load_dwordx4 v[200:203], v[242:243], off
	global_load_dwordx4 v[222:225], v[242:243], off offset:256
	v_add_co_u32_e32 v242, vcc, s93, v162
	v_addc_co_u32_e32 v243, vcc, 0, v163, vcc
	global_load_dwordx4 v[226:229], v[242:243], off
	global_load_dwordx4 v[230:233], v[242:243], off offset:256
	v_add_co_u32_e32 v242, vcc, s49, v162
	v_addc_co_u32_e32 v243, vcc, 0, v163, vcc
	global_load_dwordx4 v[234:237], v[242:243], off
	global_load_dwordx4 v[238:241], v[242:243], off offset:256
	v_lshl_add_u64 v[166:167], s[10:11], 0, v[166:167]
	v_lshl_add_u64 v[160:161], v[166:167], 0, v[160:161]
	v_readlane_b32 s90, v254, 50
	s_mov_b64 s[42:43], -1
	v_readlane_b32 s91, v254, 51
	s_and_b64 vcc, exec, s[12:13]
	s_cbranch_vccz .LBB0_939
	s_barrier
.LBB0_939:
	s_waitcnt vmcnt(9)
	v_mov_b32_e32 v180, v184
	v_mov_b32_e32 v181, v185
	v_mov_b32_e32 v182, v186
	v_mov_b32_e32 v183, v187
	v_add_co_u32_e32 v242, vcc, s50, v162
	v_addc_co_u32_e32 v243, vcc, 0, v163, vcc
	global_load_dwordx4 v[184:187], v[242:243], off
	v_pk_add_f32 v[142:143], v[142:143], v[36:37]
	v_pk_add_f32 v[146:147], v[146:147], v[40:41]
	v_pk_add_f32 v[144:145], v[144:145], v[38:39]
	v_pk_add_f32 v[140:141], v[140:141], v[34:35]
	v_pk_mul_f32 v[144:145], v[144:145], s[74:75] op_sel_hi:[1,0]
	v_pk_mul_f32 v[146:147], v[146:147], s[74:75] op_sel_hi:[1,0]
	v_pk_mul_f32 v[140:141], v[140:141], s[74:75] op_sel_hi:[1,0]
	v_pk_mul_f32 v[142:143], v[142:143], s[74:75] op_sel_hi:[1,0]
	v_exp_f32_e32 v144, v144
	v_exp_f32_e32 v145, v145
	v_exp_f32_e32 v146, v146
	v_exp_f32_e32 v147, v147
	v_exp_f32_e32 v140, v140
	v_exp_f32_e32 v141, v141
	v_exp_f32_e32 v142, v142
	v_exp_f32_e32 v143, v143
	v_pk_add_f32 v[144:145], v[144:145], 1.0 op_sel_hi:[1,0]
	v_pk_add_f32 v[146:147], v[146:147], 1.0 op_sel_hi:[1,0]
	v_pk_add_f32 v[140:141], v[140:141], 1.0 op_sel_hi:[1,0]
	v_pk_add_f32 v[142:143], v[142:143], 1.0 op_sel_hi:[1,0]
	v_rcp_f32_e32 v144, v144
	v_rcp_f32_e32 v145, v145
	v_rcp_f32_e32 v146, v146
	v_rcp_f32_e32 v147, v147
	v_rcp_f32_e32 v140, v140
	v_rcp_f32_e32 v141, v141
	v_rcp_f32_e32 v142, v142
	v_rcp_f32_e32 v143, v143
	v_lshlrev_b32_e32 v166, 16, v180
	v_and_b32_e32 v167, 0xffff0000, v180
	v_lshlrev_b32_e32 v168, 16, v181
	v_and_b32_e32 v169, 0xffff0000, v181
	v_lshlrev_b32_e32 v172, 16, v182
	v_and_b32_e32 v173, 0xffff0000, v182
	v_lshlrev_b32_e32 v180, 16, v183
	v_and_b32_e32 v181, 0xffff0000, v183
	v_pk_mul_f32 v[146:147], v[146:147], v[168:169]
	v_pk_mul_f32 v[144:145], v[144:145], v[166:167]
	v_pk_mul_f32 v[166:167], v[142:143], v[180:181]
	v_pk_mul_f32 v[142:143], v[140:141], v[172:173]
	v_cvt_pk_bf16_f32 v140, v144, v145
	v_cvt_pk_bf16_f32 v141, v146, v147
	v_cvt_pk_bf16_f32 v142, v142, v143
	v_cvt_pk_bf16_f32 v143, v166, v167
	global_store_dwordx4 v[160:161], v[140:143], off
	v_pk_add_f32 v[138:139], v[138:139], v[24:25]
	v_pk_add_f32 v[136:137], v[136:137], v[22:23]
	v_pk_add_f32 v[134:135], v[134:135], v[16:17]
	v_pk_add_f32 v[132:133], v[132:133], v[14:15]
	v_pk_mul_f32 v[136:137], v[136:137], s[74:75] op_sel_hi:[1,0]
	v_pk_mul_f32 v[138:139], v[138:139], s[74:75] op_sel_hi:[1,0]
	v_pk_mul_f32 v[132:133], v[132:133], s[74:75] op_sel_hi:[1,0]
	v_pk_mul_f32 v[134:135], v[134:135], s[74:75] op_sel_hi:[1,0]
	v_exp_f32_e32 v136, v136
	v_exp_f32_e32 v137, v137
	v_exp_f32_e32 v138, v138
	v_exp_f32_e32 v139, v139
	v_exp_f32_e32 v132, v132
	v_exp_f32_e32 v133, v133
	v_exp_f32_e32 v134, v134
	v_exp_f32_e32 v135, v135
	v_pk_add_f32 v[136:137], v[136:137], 1.0 op_sel_hi:[1,0]
	v_pk_add_f32 v[138:139], v[138:139], 1.0 op_sel_hi:[1,0]
	v_pk_add_f32 v[132:133], v[132:133], 1.0 op_sel_hi:[1,0]
	v_pk_add_f32 v[134:135], v[134:135], 1.0 op_sel_hi:[1,0]
	v_rcp_f32_e32 v136, v136
	v_rcp_f32_e32 v137, v137
	v_rcp_f32_e32 v138, v138
	v_rcp_f32_e32 v139, v139
	v_rcp_f32_e32 v132, v132
	v_rcp_f32_e32 v133, v133
	v_rcp_f32_e32 v134, v134
	v_rcp_f32_e32 v135, v135
	v_pk_add_f32 v[128:129], v[128:129], v[38:39]
	v_pk_add_f32 v[124:125], v[124:125], v[34:35]
	v_pk_add_f32 v[130:131], v[130:131], v[40:41]
	v_pk_mul_f32 v[128:129], v[128:129], s[74:75] op_sel_hi:[1,0]
	v_pk_add_f32 v[126:127], v[126:127], v[36:37]
	v_pk_mul_f32 v[124:125], v[124:125], s[74:75] op_sel_hi:[1,0]
	v_pk_mul_f32 v[130:131], v[130:131], s[74:75] op_sel_hi:[1,0]
	v_exp_f32_e32 v128, v128
	v_exp_f32_e32 v129, v129
	v_pk_mul_f32 v[126:127], v[126:127], s[74:75] op_sel_hi:[1,0]
	v_exp_f32_e32 v124, v124
	v_exp_f32_e32 v125, v125
	v_exp_f32_e32 v130, v130
	v_exp_f32_e32 v131, v131
	v_exp_f32_e32 v126, v126
	v_exp_f32_e32 v127, v127
	v_pk_add_f32 v[128:129], v[128:129], 1.0 op_sel_hi:[1,0]
	v_pk_add_f32 v[124:125], v[124:125], 1.0 op_sel_hi:[1,0]
	v_pk_add_f32 v[130:131], v[130:131], 1.0 op_sel_hi:[1,0]
	v_rcp_f32_e32 v128, v128
	v_rcp_f32_e32 v129, v129
	v_pk_add_f32 v[126:127], v[126:127], 1.0 op_sel_hi:[1,0]
	v_rcp_f32_e32 v124, v124
	v_rcp_f32_e32 v125, v125
	v_rcp_f32_e32 v130, v130
	v_rcp_f32_e32 v131, v131
	v_rcp_f32_e32 v126, v126
	v_rcp_f32_e32 v127, v127
	v_pk_add_f32 v[122:123], v[122:123], v[24:25]
	v_pk_add_f32 v[120:121], v[120:121], v[22:23]
	v_pk_add_f32 v[118:119], v[118:119], v[16:17]
	v_pk_add_f32 v[116:117], v[116:117], v[14:15]
	v_pk_mul_f32 v[120:121], v[120:121], s[74:75] op_sel_hi:[1,0]
	v_pk_mul_f32 v[122:123], v[122:123], s[74:75] op_sel_hi:[1,0]
	v_pk_mul_f32 v[116:117], v[116:117], s[74:75] op_sel_hi:[1,0]
	v_pk_mul_f32 v[118:119], v[118:119], s[74:75] op_sel_hi:[1,0]
	v_exp_f32_e32 v120, v120
	v_exp_f32_e32 v121, v121
	v_exp_f32_e32 v122, v122
	v_exp_f32_e32 v123, v123
	v_exp_f32_e32 v116, v116
	v_exp_f32_e32 v117, v117
	v_exp_f32_e32 v118, v118
	v_exp_f32_e32 v119, v119
	v_pk_add_f32 v[120:121], v[120:121], 1.0 op_sel_hi:[1,0]
	v_pk_add_f32 v[122:123], v[122:123], 1.0 op_sel_hi:[1,0]
	v_pk_add_f32 v[116:117], v[116:117], 1.0 op_sel_hi:[1,0]
	v_pk_add_f32 v[118:119], v[118:119], 1.0 op_sel_hi:[1,0]
	v_rcp_f32_e32 v120, v120
	v_rcp_f32_e32 v121, v121
	v_rcp_f32_e32 v122, v122
	s_waitcnt vmcnt(10)
; #define GAS __attribute__((address_space(1)))
; __device__ __forceinline__ u32x4 pack8(f32x4 v0, f32x4 v1) { u32x4 w; w.x = cvt_pk_bf16(v0[0], v0[1]); w.y = cvt_pk_bf16(v0[2], v0[3]); w.z = cvt_pk_bf16(v1[0], v1[1]); w.w = cvt_pk_bf16(v1[2], v1[3]); return w; }
; __device__ __forceinline__ void unpack8(u32x4 w, f32x4& v0, f32x4& v1) { v0 = (f32x4){bflo(w.x), bfhi(w.x), bflo(w.y), bfhi(w.y)}; v1 = (f32x4){bflo(w.z), bfhi(w.z), bflo(w.w), bfhi(w.w)}; }
; #define GAS __attribute__((address_space(1)))
;     __device__ __forceinline__ void operator()(const f32x4 (&acc)[2][2][4][2], const Unit& u, int wr, int wc, int fr, int fq) const {
;     ...
;         const bf16_t* const zb = Z + (size_t)row0 * 1024 + col0; bf16_t* const sob = SO + (size_t)row0 * 1024 + col0;
; #pragma unroll
;         for (int ai = 0; ai < 2; ++ai)
; #pragma unroll
;             for (int m = 0; m < 4; ++m) { const size_t off = (size_t)(ai * HALF + m * 16) * 1024;
; #pragma unroll
;                 for (int bj = 0; bj < 2; ++bj) { f32x4 z0, z1; unpack8(*(const GAS u32x4*)(zb + off + bj * HALF), z0, z1);
;                     const f32x4 v0 = z0 * sigmoid4(acc[ai][bj][m][0] + bv[bj][0]), v1 = z1 * sigmoid4(acc[ai][bj][m][1] + bv[bj][1]);
;                     *(GAS u32x4*)(sob + off + bj * HALF) = pack8(v0, v1); } }
	v_mov_b32_e32 v140, v188
	v_mov_b32_e32 v141, v189
	v_mov_b32_e32 v142, v190
	v_mov_b32_e32 v143, v191
	global_load_dwordx4 v[188:191], v[242:243], off offset:256
	v_lshlrev_b32_e32 v144, 16, v140
	v_and_b32_e32 v145, 0xffff0000, v140
	v_lshlrev_b32_e32 v140, 16, v141
	v_and_b32_e32 v141, 0xffff0000, v141
	v_lshlrev_b32_e32 v146, 16, v142
	v_and_b32_e32 v147, 0xffff0000, v142
	v_lshlrev_b32_e32 v142, 16, v143
	v_and_b32_e32 v143, 0xffff0000, v143
	v_pk_mul_f32 v[138:139], v[138:139], v[140:141]
	v_pk_mul_f32 v[136:137], v[136:137], v[144:145]
	v_pk_mul_f32 v[140:141], v[134:135], v[142:143]
	v_pk_mul_f32 v[134:135], v[132:133], v[146:147]
	v_cvt_pk_bf16_f32 v132, v136, v137
	v_cvt_pk_bf16_f32 v133, v138, v139
	v_cvt_pk_bf16_f32 v134, v134, v135
	v_cvt_pk_bf16_f32 v135, v140, v141
	global_store_dwordx4 v[160:161], v[132:135], off offset:256
	v_rcp_f32_e32 v123, v123
	v_rcp_f32_e32 v116, v116
	v_add_co_u32_e32 v132, vcc, s94, v162
	v_rcp_f32_e32 v117, v117
	s_nop 0
	v_addc_co_u32_e32 v133, vcc, 0, v163, vcc
	v_rcp_f32_e32 v118, v118
	v_rcp_f32_e32 v119, v119
	v_pk_add_f32 v[112:113], v[112:113], v[38:39]
	v_pk_add_f32 v[108:109], v[108:109], v[34:35]
	v_pk_add_f32 v[114:115], v[114:115], v[40:41]
	v_pk_mul_f32 v[112:113], v[112:113], s[74:75] op_sel_hi:[1,0]
	v_pk_add_f32 v[110:111], v[110:111], v[36:37]
	v_pk_mul_f32 v[108:109], v[108:109], s[74:75] op_sel_hi:[1,0]
	v_pk_mul_f32 v[114:115], v[114:115], s[74:75] op_sel_hi:[1,0]
	v_exp_f32_e32 v112, v112
	v_exp_f32_e32 v113, v113
	v_pk_mul_f32 v[110:111], v[110:111], s[74:75] op_sel_hi:[1,0]
	v_exp_f32_e32 v108, v108
	v_exp_f32_e32 v109, v109
	v_exp_f32_e32 v114, v114
	v_exp_f32_e32 v115, v115
	v_exp_f32_e32 v110, v110
	v_exp_f32_e32 v111, v111
	v_pk_add_f32 v[112:113], v[112:113], 1.0 op_sel_hi:[1,0]
	v_pk_add_f32 v[108:109], v[108:109], 1.0 op_sel_hi:[1,0]
	v_pk_add_f32 v[114:115], v[114:115], 1.0 op_sel_hi:[1,0]
	v_rcp_f32_e32 v112, v112
	v_rcp_f32_e32 v113, v113
	v_pk_add_f32 v[110:111], v[110:111], 1.0 op_sel_hi:[1,0]
	v_rcp_f32_e32 v108, v108
	v_rcp_f32_e32 v109, v109
	v_rcp_f32_e32 v114, v114
	v_rcp_f32_e32 v115, v115
	v_rcp_f32_e32 v110, v110
	v_rcp_f32_e32 v111, v111
	v_pk_add_f32 v[106:107], v[106:107], v[24:25]
	v_pk_add_f32 v[104:105], v[104:105], v[22:23]
	v_pk_add_f32 v[102:103], v[102:103], v[16:17]
	v_pk_add_f32 v[100:101], v[100:101], v[14:15]
	v_pk_mul_f32 v[104:105], v[104:105], s[74:75] op_sel_hi:[1,0]
	v_pk_mul_f32 v[106:107], v[106:107], s[74:75] op_sel_hi:[1,0]
	v_pk_mul_f32 v[100:101], v[100:101], s[74:75] op_sel_hi:[1,0]
	v_pk_mul_f32 v[102:103], v[102:103], s[74:75] op_sel_hi:[1,0]
	v_exp_f32_e32 v104, v104
	v_exp_f32_e32 v105, v105
	v_exp_f32_e32 v106, v106
	v_exp_f32_e32 v107, v107
	v_exp_f32_e32 v100, v100
	v_exp_f32_e32 v101, v101
	v_exp_f32_e32 v102, v102
	v_exp_f32_e32 v103, v103
	v_pk_add_f32 v[104:105], v[104:105], 1.0 op_sel_hi:[1,0]
	v_pk_add_f32 v[106:107], v[106:107], 1.0 op_sel_hi:[1,0]
	v_pk_add_f32 v[100:101], v[100:101], 1.0 op_sel_hi:[1,0]
	v_pk_add_f32 v[102:103], v[102:103], 1.0 op_sel_hi:[1,0]
	v_rcp_f32_e32 v104, v104
	v_rcp_f32_e32 v105, v105
	v_rcp_f32_e32 v106, v106
	v_rcp_f32_e32 v107, v107
	v_rcp_f32_e32 v100, v100
	v_rcp_f32_e32 v101, v101
	v_rcp_f32_e32 v102, v102
	v_rcp_f32_e32 v103, v103
	v_pk_add_f32 v[94:95], v[94:95], v[38:39]
	v_pk_add_f32 v[90:91], v[90:91], v[34:35]
	v_pk_add_f32 v[96:97], v[96:97], v[40:41]
	v_pk_mul_f32 v[94:95], v[94:95], s[74:75] op_sel_hi:[1,0]
	v_pk_add_f32 v[92:93], v[92:93], v[36:37]
	v_pk_mul_f32 v[90:91], v[90:91], s[74:75] op_sel_hi:[1,0]
	v_pk_mul_f32 v[96:97], v[96:97], s[74:75] op_sel_hi:[1,0]
	v_exp_f32_e32 v94, v94
	v_exp_f32_e32 v95, v95
	v_pk_mul_f32 v[92:93], v[92:93], s[74:75] op_sel_hi:[1,0]
	v_exp_f32_e32 v90, v90
	v_exp_f32_e32 v91, v91
	v_exp_f32_e32 v96, v96
	v_exp_f32_e32 v97, v97
	v_exp_f32_e32 v92, v92
	v_exp_f32_e32 v93, v93
	v_pk_add_f32 v[94:95], v[94:95], 1.0 op_sel_hi:[1,0]
	v_pk_add_f32 v[90:91], v[90:91], 1.0 op_sel_hi:[1,0]
	v_pk_add_f32 v[96:97], v[96:97], 1.0 op_sel_hi:[1,0]
	v_rcp_f32_e32 v94, v94
	v_rcp_f32_e32 v95, v95
	s_waitcnt vmcnt(11)
	v_mov_b32_e32 v134, v192
	v_mov_b32_e32 v135, v193
	v_mov_b32_e32 v136, v194
	v_mov_b32_e32 v137, v195
	v_add_co_u32_e32 v242, vcc, s51, v162
	v_addc_co_u32_e32 v243, vcc, 0, v163, vcc
	global_load_dwordx4 v[192:195], v[242:243], off
	v_lshlrev_b32_e32 v138, 16, v134
	v_and_b32_e32 v139, 0xffff0000, v134
	v_lshlrev_b32_e32 v140, 16, v136
	v_and_b32_e32 v141, 0xffff0000, v136
	v_lshlrev_b32_e32 v134, 16, v135
	v_and_b32_e32 v135, 0xffff0000, v135
	v_lshlrev_b32_e32 v136, 16, v137
	v_and_b32_e32 v137, 0xffff0000, v137
	v_pk_mul_f32 v[128:129], v[128:129], v[138:139]
	v_pk_mul_f32 v[124:125], v[124:125], v[140:141]
	v_pk_mul_f32 v[130:131], v[130:131], v[134:135]
	v_pk_mul_f32 v[134:135], v[126:127], v[136:137]
	v_cvt_pk_bf16_f32 v126, v128, v129
	v_cvt_pk_bf16_f32 v128, v124, v125
	v_add_co_u32_e32 v124, vcc, s94, v160
	v_cvt_pk_bf16_f32 v127, v130, v131
	v_cvt_pk_bf16_f32 v129, v134, v135
	v_addc_co_u32_e32 v125, vcc, 0, v161, vcc
	global_store_dwordx4 v[124:125], v[126:129], off
	v_pk_add_f32 v[92:93], v[92:93], 1.0 op_sel_hi:[1,0]
	v_rcp_f32_e32 v90, v90
	v_rcp_f32_e32 v91, v91
	v_rcp_f32_e32 v96, v96
	v_rcp_f32_e32 v97, v97
	v_rcp_f32_e32 v92, v92
	v_rcp_f32_e32 v93, v93
	v_pk_add_f32 v[88:89], v[88:89], v[24:25]
	v_pk_add_f32 v[86:87], v[86:87], v[22:23]
	v_pk_add_f32 v[84:85], v[84:85], v[16:17]
	v_pk_add_f32 v[82:83], v[82:83], v[14:15]
	v_pk_mul_f32 v[86:87], v[86:87], s[74:75] op_sel_hi:[1,0]
	v_pk_mul_f32 v[88:89], v[88:89], s[74:75] op_sel_hi:[1,0]
	v_pk_mul_f32 v[82:83], v[82:83], s[74:75] op_sel_hi:[1,0]
; #define GAS __attribute__((address_space(1)))
; __device__ __forceinline__ u32x4 pack8(f32x4 v0, f32x4 v1) { u32x4 w; w.x = cvt_pk_bf16(v0[0], v0[1]); w.y = cvt_pk_bf16(v0[2], v0[3]); w.z = cvt_pk_bf16(v1[0], v1[1]); w.w = cvt_pk_bf16(v1[2], v1[3]); return w; }
; __device__ __forceinline__ void unpack8(u32x4 w, f32x4& v0, f32x4& v1) { v0 = (f32x4){bflo(w.x), bfhi(w.x), bflo(w.y), bfhi(w.y)}; v1 = (f32x4){bflo(w.z), bfhi(w.z), bflo(w.w), bfhi(w.w)}; }
; #define GAS __attribute__((address_space(1)))
;     __device__ __forceinline__ void operator()(const f32x4 (&acc)[2][2][4][2], const Unit& u, int wr, int wc, int fr, int fq) const {
;     ...
;         const bf16_t* const zb = Z + (size_t)row0 * 1024 + col0; bf16_t* const sob = SO + (size_t)row0 * 1024 + col0;
; #pragma unroll
;         for (int ai = 0; ai < 2; ++ai)
; #pragma unroll
;             for (int m = 0; m < 4; ++m) { const size_t off = (size_t)(ai * HALF + m * 16) * 1024;
; #pragma unroll
;                 for (int bj = 0; bj < 2; ++bj) { f32x4 z0, z1; unpack8(*(const GAS u32x4*)(zb + off + bj * HALF), z0, z1);
;                     const f32x4 v0 = z0 * sigmoid4(acc[ai][bj][m][0] + bv[bj][0]), v1 = z1 * sigmoid4(acc[ai][bj][m][1] + bv[bj][1]);
;                     *(GAS u32x4*)(sob + off + bj * HALF) = pack8(v0, v1); } }
	v_pk_mul_f32 v[84:85], v[84:85], s[74:75] op_sel_hi:[1,0]
	v_exp_f32_e32 v86, v86
	v_exp_f32_e32 v87, v87
	v_exp_f32_e32 v88, v88
	v_exp_f32_e32 v89, v89
	v_exp_f32_e32 v82, v82
	v_exp_f32_e32 v83, v83
	v_exp_f32_e32 v84, v84
	v_exp_f32_e32 v85, v85
	v_pk_add_f32 v[86:87], v[86:87], 1.0 op_sel_hi:[1,0]
	v_pk_add_f32 v[88:89], v[88:89], 1.0 op_sel_hi:[1,0]
	v_pk_add_f32 v[82:83], v[82:83], 1.0 op_sel_hi:[1,0]
	v_pk_add_f32 v[84:85], v[84:85], 1.0 op_sel_hi:[1,0]
	v_rcp_f32_e32 v86, v86
	v_rcp_f32_e32 v87, v87
	v_rcp_f32_e32 v88, v88
	v_rcp_f32_e32 v89, v89
	v_rcp_f32_e32 v82, v82
	v_rcp_f32_e32 v83, v83
	v_rcp_f32_e32 v84, v84
	v_rcp_f32_e32 v85, v85
	v_pk_add_f32 v[78:79], v[78:79], v[38:39]
	v_pk_add_f32 v[74:75], v[74:75], v[34:35]
	v_pk_add_f32 v[80:81], v[80:81], v[40:41]
	v_pk_mul_f32 v[78:79], v[78:79], s[74:75] op_sel_hi:[1,0]
	v_pk_add_f32 v[76:77], v[76:77], v[36:37]
	v_pk_mul_f32 v[74:75], v[74:75], s[74:75] op_sel_hi:[1,0]
	v_pk_mul_f32 v[80:81], v[80:81], s[74:75] op_sel_hi:[1,0]
	v_exp_f32_e32 v78, v78
	v_exp_f32_e32 v79, v79
	v_pk_mul_f32 v[76:77], v[76:77], s[74:75] op_sel_hi:[1,0]
	v_exp_f32_e32 v74, v74
	v_exp_f32_e32 v75, v75
	v_exp_f32_e32 v80, v80
	v_exp_f32_e32 v81, v81
	v_exp_f32_e32 v76, v76
	v_exp_f32_e32 v77, v77
	v_pk_add_f32 v[78:79], v[78:79], 1.0 op_sel_hi:[1,0]
	v_pk_add_f32 v[74:75], v[74:75], 1.0 op_sel_hi:[1,0]
	v_pk_add_f32 v[80:81], v[80:81], 1.0 op_sel_hi:[1,0]
	v_rcp_f32_e32 v78, v78
	v_rcp_f32_e32 v79, v79
	v_pk_add_f32 v[76:77], v[76:77], 1.0 op_sel_hi:[1,0]
	v_rcp_f32_e32 v74, v74
	v_rcp_f32_e32 v75, v75
	v_rcp_f32_e32 v80, v80
	v_rcp_f32_e32 v81, v81
	v_rcp_f32_e32 v76, v76
	v_rcp_f32_e32 v77, v77
	v_pk_add_f32 v[72:73], v[72:73], v[24:25]
	v_pk_add_f32 v[70:71], v[70:71], v[22:23]
	v_pk_add_f32 v[68:69], v[68:69], v[16:17]
	v_pk_add_f32 v[66:67], v[66:67], v[14:15]
	v_pk_mul_f32 v[70:71], v[70:71], s[74:75] op_sel_hi:[1,0]
	v_pk_mul_f32 v[72:73], v[72:73], s[74:75] op_sel_hi:[1,0]
	v_pk_mul_f32 v[66:67], v[66:67], s[74:75] op_sel_hi:[1,0]
	v_pk_mul_f32 v[68:69], v[68:69], s[74:75] op_sel_hi:[1,0]
	v_exp_f32_e32 v70, v70
	v_exp_f32_e32 v71, v71
	v_exp_f32_e32 v72, v72
	v_exp_f32_e32 v73, v73
	v_exp_f32_e32 v66, v66
	v_exp_f32_e32 v67, v67
	v_exp_f32_e32 v68, v68
	v_exp_f32_e32 v69, v69
	s_waitcnt vmcnt(12)
	v_mov_b32_e32 v126, v196
	v_mov_b32_e32 v127, v197
	v_mov_b32_e32 v128, v198
	v_mov_b32_e32 v129, v199
	global_load_dwordx4 v[196:199], v[242:243], off offset:256
	v_lshlrev_b32_e32 v130, 16, v126
	v_and_b32_e32 v131, 0xffff0000, v126
	v_lshlrev_b32_e32 v126, 16, v127
	v_and_b32_e32 v127, 0xffff0000, v127
	v_lshlrev_b32_e32 v132, 16, v128
	v_and_b32_e32 v133, 0xffff0000, v128
	v_lshlrev_b32_e32 v128, 16, v129
	v_and_b32_e32 v129, 0xffff0000, v129
	v_pk_mul_f32 v[122:123], v[122:123], v[126:127]
	v_pk_mul_f32 v[120:121], v[120:121], v[130:131]
	v_pk_mul_f32 v[126:127], v[118:119], v[128:129]
	v_pk_mul_f32 v[118:119], v[116:117], v[132:133]
	v_cvt_pk_bf16_f32 v116, v120, v121
	v_cvt_pk_bf16_f32 v117, v122, v123
	v_cvt_pk_bf16_f32 v118, v118, v119
	v_cvt_pk_bf16_f32 v119, v126, v127
	global_store_dwordx4 v[124:125], v[116:119], off offset:256
	v_pk_add_f32 v[70:71], v[70:71], 1.0 op_sel_hi:[1,0]
	v_pk_add_f32 v[72:73], v[72:73], 1.0 op_sel_hi:[1,0]
	v_add_co_u32_e32 v116, vcc, s73, v162
	v_pk_add_f32 v[66:67], v[66:67], 1.0 op_sel_hi:[1,0]
	s_nop 0
	v_addc_co_u32_e32 v117, vcc, 0, v163, vcc
	v_pk_add_f32 v[68:69], v[68:69], 1.0 op_sel_hi:[1,0]
	v_rcp_f32_e32 v70, v70
	v_rcp_f32_e32 v71, v71
	v_rcp_f32_e32 v72, v72
	v_rcp_f32_e32 v73, v73
	v_rcp_f32_e32 v66, v66
	v_rcp_f32_e32 v67, v67
	v_rcp_f32_e32 v68, v68
	v_rcp_f32_e32 v69, v69
	v_pk_add_f32 v[62:63], v[62:63], v[38:39]
	v_pk_add_f32 v[58:59], v[58:59], v[34:35]
	v_pk_add_f32 v[64:65], v[64:65], v[40:41]
	v_pk_mul_f32 v[62:63], v[62:63], s[74:75] op_sel_hi:[1,0]
	v_pk_add_f32 v[60:61], v[60:61], v[36:37]
	v_pk_mul_f32 v[58:59], v[58:59], s[74:75] op_sel_hi:[1,0]
	v_pk_mul_f32 v[64:65], v[64:65], s[74:75] op_sel_hi:[1,0]
	v_exp_f32_e32 v62, v62
	v_exp_f32_e32 v63, v63
	v_pk_mul_f32 v[60:61], v[60:61], s[74:75] op_sel_hi:[1,0]
	v_exp_f32_e32 v58, v58
	v_exp_f32_e32 v59, v59
	v_exp_f32_e32 v64, v64
	v_exp_f32_e32 v65, v65
	v_exp_f32_e32 v60, v60
	v_exp_f32_e32 v61, v61
	v_pk_add_f32 v[62:63], v[62:63], 1.0 op_sel_hi:[1,0]
	v_pk_add_f32 v[58:59], v[58:59], 1.0 op_sel_hi:[1,0]
	v_pk_add_f32 v[64:65], v[64:65], 1.0 op_sel_hi:[1,0]
	v_rcp_f32_e32 v62, v62
	v_rcp_f32_e32 v63, v63
	v_pk_add_f32 v[60:61], v[60:61], 1.0 op_sel_hi:[1,0]
	v_rcp_f32_e32 v58, v58
	v_rcp_f32_e32 v59, v59
	v_rcp_f32_e32 v64, v64
	v_rcp_f32_e32 v65, v65
	v_rcp_f32_e32 v60, v60
	v_rcp_f32_e32 v61, v61
	v_pk_add_f32 v[56:57], v[56:57], v[24:25]
	v_pk_add_f32 v[54:55], v[54:55], v[22:23]
	v_pk_add_f32 v[52:53], v[52:53], v[16:17]
	v_pk_add_f32 v[50:51], v[50:51], v[14:15]
	v_pk_mul_f32 v[54:55], v[54:55], s[74:75] op_sel_hi:[1,0]
	v_pk_mul_f32 v[56:57], v[56:57], s[74:75] op_sel_hi:[1,0]
	v_pk_mul_f32 v[50:51], v[50:51], s[74:75] op_sel_hi:[1,0]
	v_pk_mul_f32 v[52:53], v[52:53], s[74:75] op_sel_hi:[1,0]
	v_exp_f32_e32 v54, v54
	v_exp_f32_e32 v55, v55
	v_exp_f32_e32 v56, v56
	v_exp_f32_e32 v57, v57
	v_exp_f32_e32 v50, v50
	v_exp_f32_e32 v51, v51
	v_exp_f32_e32 v52, v52
	v_exp_f32_e32 v53, v53
	v_pk_add_f32 v[54:55], v[54:55], 1.0 op_sel_hi:[1,0]
	v_pk_add_f32 v[56:57], v[56:57], 1.0 op_sel_hi:[1,0]
	v_pk_add_f32 v[50:51], v[50:51], 1.0 op_sel_hi:[1,0]
	v_pk_add_f32 v[52:53], v[52:53], 1.0 op_sel_hi:[1,0]
	v_rcp_f32_e32 v54, v54
	v_rcp_f32_e32 v55, v55
	v_rcp_f32_e32 v56, v56
	v_rcp_f32_e32 v57, v57
	v_rcp_f32_e32 v50, v50
	v_rcp_f32_e32 v51, v51
	v_rcp_f32_e32 v52, v52
	v_rcp_f32_e32 v53, v53
	v_pk_add_f32 v[46:47], v[46:47], v[38:39]
	v_pk_add_f32 v[42:43], v[42:43], v[34:35]
	v_pk_add_f32 v[48:49], v[48:49], v[40:41]
	v_pk_mul_f32 v[46:47], v[46:47], s[74:75] op_sel_hi:[1,0]
	v_pk_add_f32 v[44:45], v[44:45], v[36:37]
	v_pk_mul_f32 v[42:43], v[42:43], s[74:75] op_sel_hi:[1,0]
	v_pk_mul_f32 v[48:49], v[48:49], s[74:75] op_sel_hi:[1,0]
	v_exp_f32_e32 v46, v46
	v_exp_f32_e32 v47, v47
	v_pk_mul_f32 v[44:45], v[44:45], s[74:75] op_sel_hi:[1,0]
	v_exp_f32_e32 v42, v42
	v_exp_f32_e32 v43, v43
	v_exp_f32_e32 v48, v48
	v_exp_f32_e32 v49, v49
	s_waitcnt vmcnt(13)
; #define GAS __attribute__((address_space(1)))
; __device__ __forceinline__ u32x4 pack8(f32x4 v0, f32x4 v1) { u32x4 w; w.x = cvt_pk_bf16(v0[0], v0[1]); w.y = cvt_pk_bf16(v0[2], v0[3]); w.z = cvt_pk_bf16(v1[0], v1[1]); w.w = cvt_pk_bf16(v1[2], v1[3]); return w; }
; __device__ __forceinline__ void unpack8(u32x4 w, f32x4& v0, f32x4& v1) { v0 = (f32x4){bflo(w.x), bfhi(w.x), bflo(w.y), bfhi(w.y)}; v1 = (f32x4){bflo(w.z), bfhi(w.z), bflo(w.w), bfhi(w.w)}; }
; #define GAS __attribute__((address_space(1)))
;     __device__ __forceinline__ void operator()(const f32x4 (&acc)[2][2][4][2], const Unit& u, int wr, int wc, int fr, int fq) const {
;     ...
;         const bf16_t* const zb = Z + (size_t)row0 * 1024 + col0; bf16_t* const sob = SO + (size_t)row0 * 1024 + col0;
; #pragma unroll
;         for (int ai = 0; ai < 2; ++ai)
; #pragma unroll
;             for (int m = 0; m < 4; ++m) { const size_t off = (size_t)(ai * HALF + m * 16) * 1024;
; #pragma unroll
;                 for (int bj = 0; bj < 2; ++bj) { f32x4 z0, z1; unpack8(*(const GAS u32x4*)(zb + off + bj * HALF), z0, z1);
;                     const f32x4 v0 = z0 * sigmoid4(acc[ai][bj][m][0] + bv[bj][0]), v1 = z1 * sigmoid4(acc[ai][bj][m][1] + bv[bj][1]);
;                     *(GAS u32x4*)(sob + off + bj * HALF) = pack8(v0, v1); } }
	v_mov_b32_e32 v118, v200
	v_mov_b32_e32 v119, v201
	v_mov_b32_e32 v120, v202
	v_mov_b32_e32 v121, v203
	v_add_co_u32_e32 v242, vcc, s66, v162
	v_addc_co_u32_e32 v243, vcc, 0, v163, vcc
	global_load_dwordx4 v[200:203], v[242:243], off
	v_lshlrev_b32_e32 v122, 16, v118
	v_and_b32_e32 v123, 0xffff0000, v118
	v_lshlrev_b32_e32 v124, 16, v120
	v_and_b32_e32 v125, 0xffff0000, v120
	v_lshlrev_b32_e32 v118, 16, v119
	v_and_b32_e32 v119, 0xffff0000, v119
	v_lshlrev_b32_e32 v120, 16, v121
	v_and_b32_e32 v121, 0xffff0000, v121
	v_pk_mul_f32 v[112:113], v[112:113], v[122:123]
	v_pk_mul_f32 v[108:109], v[108:109], v[124:125]
	v_pk_mul_f32 v[114:115], v[114:115], v[118:119]
	v_pk_mul_f32 v[118:119], v[110:111], v[120:121]
	v_cvt_pk_bf16_f32 v110, v112, v113
	v_cvt_pk_bf16_f32 v112, v108, v109
	v_add_co_u32_e32 v108, vcc, s73, v160
	v_cvt_pk_bf16_f32 v111, v114, v115
	v_cvt_pk_bf16_f32 v113, v118, v119
	v_addc_co_u32_e32 v109, vcc, 0, v161, vcc
	global_store_dwordx4 v[108:109], v[110:113], off
	v_exp_f32_e32 v44, v44
	v_exp_f32_e32 v45, v45
	v_pk_add_f32 v[46:47], v[46:47], 1.0 op_sel_hi:[1,0]
	v_pk_add_f32 v[42:43], v[42:43], 1.0 op_sel_hi:[1,0]
	v_pk_add_f32 v[48:49], v[48:49], 1.0 op_sel_hi:[1,0]
	v_rcp_f32_e32 v46, v46
	v_rcp_f32_e32 v47, v47
	v_pk_add_f32 v[44:45], v[44:45], 1.0 op_sel_hi:[1,0]
	v_rcp_f32_e32 v42, v42
	v_rcp_f32_e32 v43, v43
	v_rcp_f32_e32 v48, v48
	v_rcp_f32_e32 v49, v49
	v_rcp_f32_e32 v44, v44
	v_rcp_f32_e32 v45, v45
	v_pk_add_f32 v[32:33], v[32:33], v[24:25]
	v_pk_add_f32 v[30:31], v[30:31], v[22:23]
	v_pk_add_f32 v[28:29], v[28:29], v[16:17]
	v_pk_add_f32 v[26:27], v[26:27], v[14:15]
	v_pk_mul_f32 v[30:31], v[30:31], s[74:75] op_sel_hi:[1,0]
	v_pk_mul_f32 v[32:33], v[32:33], s[74:75] op_sel_hi:[1,0]
	v_pk_mul_f32 v[26:27], v[26:27], s[74:75] op_sel_hi:[1,0]
	v_pk_mul_f32 v[28:29], v[28:29], s[74:75] op_sel_hi:[1,0]
	v_exp_f32_e32 v30, v30
	v_exp_f32_e32 v31, v31
	v_exp_f32_e32 v32, v32
	v_exp_f32_e32 v33, v33
	v_exp_f32_e32 v26, v26
	v_exp_f32_e32 v27, v27
	v_exp_f32_e32 v28, v28
	v_exp_f32_e32 v29, v29
	v_pk_add_f32 v[30:31], v[30:31], 1.0 op_sel_hi:[1,0]
	v_pk_add_f32 v[32:33], v[32:33], 1.0 op_sel_hi:[1,0]
	v_pk_add_f32 v[26:27], v[26:27], 1.0 op_sel_hi:[1,0]
	v_pk_add_f32 v[28:29], v[28:29], 1.0 op_sel_hi:[1,0]
	v_rcp_f32_e32 v30, v30
	v_rcp_f32_e32 v31, v31
	v_rcp_f32_e32 v32, v32
	v_rcp_f32_e32 v33, v33
	v_rcp_f32_e32 v26, v26
	v_rcp_f32_e32 v27, v27
	v_rcp_f32_e32 v28, v28
	v_rcp_f32_e32 v29, v29
	v_pk_add_f32 v[18:19], v[18:19], v[38:39]
	v_pk_add_f32 v[20:21], v[20:21], v[40:41]
	v_pk_mul_f32 v[18:19], v[18:19], s[74:75] op_sel_hi:[1,0]
	v_pk_add_f32 v[12:13], v[12:13], v[36:37]
	v_pk_add_f32 v[10:11], v[10:11], v[34:35]
	v_pk_mul_f32 v[20:21], v[20:21], s[74:75] op_sel_hi:[1,0]
	v_exp_f32_e32 v18, v18
	v_exp_f32_e32 v19, v19
	v_pk_mul_f32 v[10:11], v[10:11], s[74:75] op_sel_hi:[1,0]
	v_pk_mul_f32 v[12:13], v[12:13], s[74:75] op_sel_hi:[1,0]
	v_exp_f32_e32 v20, v20
	v_exp_f32_e32 v21, v21
	v_exp_f32_e32 v10, v10
	v_exp_f32_e32 v11, v11
	v_exp_f32_e32 v12, v12
	v_exp_f32_e32 v13, v13
	v_pk_add_f32 v[18:19], v[18:19], 1.0 op_sel_hi:[1,0]
	v_pk_add_f32 v[20:21], v[20:21], 1.0 op_sel_hi:[1,0]
	v_rcp_f32_e32 v18, v18
	v_rcp_f32_e32 v19, v19
	v_pk_add_f32 v[10:11], v[10:11], 1.0 op_sel_hi:[1,0]
	v_pk_add_f32 v[12:13], v[12:13], 1.0 op_sel_hi:[1,0]
	v_rcp_f32_e32 v20, v20
	v_rcp_f32_e32 v21, v21
	v_rcp_f32_e32 v10, v10
	v_rcp_f32_e32 v11, v11
	v_rcp_f32_e32 v12, v12
	v_rcp_f32_e32 v13, v13
	v_pk_add_f32 v[8:9], v[8:9], v[24:25]
	v_pk_add_f32 v[6:7], v[6:7], v[22:23]
	v_pk_add_f32 v[4:5], v[4:5], v[16:17]
	v_pk_add_f32 v[2:3], v[2:3], v[14:15]
	v_pk_mul_f32 v[6:7], v[6:7], s[74:75] op_sel_hi:[1,0]
	v_pk_mul_f32 v[8:9], v[8:9], s[74:75] op_sel_hi:[1,0]
	v_pk_mul_f32 v[2:3], v[2:3], s[74:75] op_sel_hi:[1,0]
	v_pk_mul_f32 v[4:5], v[4:5], s[74:75] op_sel_hi:[1,0]
	v_exp_f32_e32 v6, v6
	s_waitcnt vmcnt(14)
	v_mov_b32_e32 v110, v222
	v_mov_b32_e32 v111, v223
	v_mov_b32_e32 v112, v224
	v_mov_b32_e32 v113, v225
	global_load_dwordx4 v[222:225], v[242:243], off offset:256
	v_lshlrev_b32_e32 v114, 16, v110
	v_and_b32_e32 v115, 0xffff0000, v110
	v_lshlrev_b32_e32 v110, 16, v111
	v_and_b32_e32 v111, 0xffff0000, v111
	v_lshlrev_b32_e32 v116, 16, v112
	v_and_b32_e32 v117, 0xffff0000, v112
	v_lshlrev_b32_e32 v112, 16, v113
	v_and_b32_e32 v113, 0xffff0000, v113
	v_pk_mul_f32 v[106:107], v[106:107], v[110:111]
	v_pk_mul_f32 v[104:105], v[104:105], v[114:115]
	v_pk_mul_f32 v[110:111], v[102:103], v[112:113]
	v_pk_mul_f32 v[102:103], v[100:101], v[116:117]
	v_cvt_pk_bf16_f32 v100, v104, v105
	v_cvt_pk_bf16_f32 v101, v106, v107
	v_cvt_pk_bf16_f32 v102, v102, v103
	v_cvt_pk_bf16_f32 v103, v110, v111
	global_store_dwordx4 v[108:109], v[100:103], off offset:256
	v_exp_f32_e32 v7, v7
	v_exp_f32_e32 v8, v8
	v_add_co_u32_e32 v100, vcc, s93, v162
	v_exp_f32_e32 v9, v9
	s_nop 0
	v_addc_co_u32_e32 v101, vcc, 0, v163, vcc
	v_exp_f32_e32 v2, v2
	v_exp_f32_e32 v3, v3
	v_exp_f32_e32 v4, v4
	v_exp_f32_e32 v5, v5
	v_pk_add_f32 v[6:7], v[6:7], 1.0 op_sel_hi:[1,0]
	v_pk_add_f32 v[8:9], v[8:9], 1.0 op_sel_hi:[1,0]
	v_pk_add_f32 v[2:3], v[2:3], 1.0 op_sel_hi:[1,0]
	v_pk_add_f32 v[4:5], v[4:5], 1.0 op_sel_hi:[1,0]
	v_rcp_f32_e32 v6, v6
	v_rcp_f32_e32 v7, v7
	v_rcp_f32_e32 v8, v8
	v_rcp_f32_e32 v9, v9
	v_rcp_f32_e32 v2, v2
	v_rcp_f32_e32 v3, v3
	v_rcp_f32_e32 v4, v4
	v_rcp_f32_e32 v5, v5
	s_waitcnt vmcnt(15)
; #define GAS __attribute__((address_space(1)))
; __device__ __forceinline__ u32x4 pack8(f32x4 v0, f32x4 v1) { u32x4 w; w.x = cvt_pk_bf16(v0[0], v0[1]); w.y = cvt_pk_bf16(v0[2], v0[3]); w.z = cvt_pk_bf16(v1[0], v1[1]); w.w = cvt_pk_bf16(v1[2], v1[3]); return w; }
; __device__ __forceinline__ void unpack8(u32x4 w, f32x4& v0, f32x4& v1) { v0 = (f32x4){bflo(w.x), bfhi(w.x), bflo(w.y), bfhi(w.y)}; v1 = (f32x4){bflo(w.z), bfhi(w.z), bflo(w.w), bfhi(w.w)}; }
; #define GAS __attribute__((address_space(1)))
;     __device__ __forceinline__ void operator()(const f32x4 (&acc)[2][2][4][2], const Unit& u, int wr, int wc, int fr, int fq) const {
;     ...
;         const bf16_t* const zb = Z + (size_t)row0 * 1024 + col0; bf16_t* const sob = SO + (size_t)row0 * 1024 + col0;
; #pragma unroll
;         for (int ai = 0; ai < 2; ++ai)
; #pragma unroll
;             for (int m = 0; m < 4; ++m) { const size_t off = (size_t)(ai * HALF + m * 16) * 1024;
; #pragma unroll
;                 for (int bj = 0; bj < 2; ++bj) { f32x4 z0, z1; unpack8(*(const GAS u32x4*)(zb + off + bj * HALF), z0, z1);
;                     const f32x4 v0 = z0 * sigmoid4(acc[ai][bj][m][0] + bv[bj][0]), v1 = z1 * sigmoid4(acc[ai][bj][m][1] + bv[bj][1]);
;                     *(GAS u32x4*)(sob + off + bj * HALF) = pack8(v0, v1); } }
	v_mov_b32_e32 v102, v226
	v_mov_b32_e32 v103, v227
	v_mov_b32_e32 v104, v228
	v_mov_b32_e32 v105, v229
	v_lshlrev_b32_e32 v106, 16, v102
	v_and_b32_e32 v107, 0xffff0000, v102
	v_lshlrev_b32_e32 v108, 16, v104
	v_and_b32_e32 v109, 0xffff0000, v104
	v_lshlrev_b32_e32 v102, 16, v103
	v_and_b32_e32 v103, 0xffff0000, v103
	v_lshlrev_b32_e32 v104, 16, v105
	v_and_b32_e32 v105, 0xffff0000, v105
	v_pk_mul_f32 v[94:95], v[94:95], v[106:107]
	v_pk_mul_f32 v[90:91], v[90:91], v[108:109]
	v_pk_mul_f32 v[96:97], v[96:97], v[102:103]
	v_pk_mul_f32 v[102:103], v[92:93], v[104:105]
	v_cvt_pk_bf16_f32 v92, v94, v95
	v_cvt_pk_bf16_f32 v94, v90, v91
	v_add_co_u32_e32 v90, vcc, s93, v160
	v_cvt_pk_bf16_f32 v93, v96, v97
	v_cvt_pk_bf16_f32 v95, v102, v103
	v_addc_co_u32_e32 v91, vcc, 0, v161, vcc
	global_store_dwordx4 v[90:91], v[92:95], off
	s_waitcnt vmcnt(15)
	v_mov_b32_e32 v92, v230
	v_mov_b32_e32 v93, v231
	v_mov_b32_e32 v94, v232
	v_mov_b32_e32 v95, v233
	v_lshlrev_b32_e32 v96, 16, v92
	v_and_b32_e32 v97, 0xffff0000, v92
	v_lshlrev_b32_e32 v92, 16, v93
	v_and_b32_e32 v93, 0xffff0000, v93
	v_lshlrev_b32_e32 v100, 16, v94
	v_and_b32_e32 v101, 0xffff0000, v94
	v_lshlrev_b32_e32 v94, 16, v95
	v_and_b32_e32 v95, 0xffff0000, v95
	v_pk_mul_f32 v[88:89], v[88:89], v[92:93]
	v_pk_mul_f32 v[86:87], v[86:87], v[96:97]
	v_pk_mul_f32 v[92:93], v[84:85], v[94:95]
	v_pk_mul_f32 v[84:85], v[82:83], v[100:101]
	v_cvt_pk_bf16_f32 v82, v86, v87
	v_cvt_pk_bf16_f32 v83, v88, v89
	v_cvt_pk_bf16_f32 v84, v84, v85
	v_cvt_pk_bf16_f32 v85, v92, v93
	global_store_dwordx4 v[90:91], v[82:85], off offset:256
	s_nop 1
	v_add_co_u32_e32 v82, vcc, s49, v162
	s_nop 1
	v_addc_co_u32_e32 v83, vcc, 0, v163, vcc
	s_waitcnt vmcnt(15)
	v_mov_b32_e32 v84, v234
	v_mov_b32_e32 v85, v235
	v_mov_b32_e32 v86, v236
	v_mov_b32_e32 v87, v237
	v_lshlrev_b32_e32 v88, 16, v84
	v_and_b32_e32 v89, 0xffff0000, v84
	v_lshlrev_b32_e32 v90, 16, v86
	v_and_b32_e32 v91, 0xffff0000, v86
	v_lshlrev_b32_e32 v84, 16, v85
	v_and_b32_e32 v85, 0xffff0000, v85
	v_lshlrev_b32_e32 v86, 16, v87
	v_and_b32_e32 v87, 0xffff0000, v87
	v_pk_mul_f32 v[78:79], v[78:79], v[88:89]
	v_pk_mul_f32 v[74:75], v[74:75], v[90:91]
	v_pk_mul_f32 v[80:81], v[80:81], v[84:85]
	v_pk_mul_f32 v[84:85], v[76:77], v[86:87]
	v_cvt_pk_bf16_f32 v76, v78, v79
	v_cvt_pk_bf16_f32 v78, v74, v75
	v_add_co_u32_e32 v74, vcc, s49, v160
	v_cvt_pk_bf16_f32 v77, v80, v81
	v_cvt_pk_bf16_f32 v79, v84, v85
	v_addc_co_u32_e32 v75, vcc, 0, v161, vcc
	global_store_dwordx4 v[74:75], v[76:79], off
	s_waitcnt vmcnt(15)
	v_mov_b32_e32 v76, v238
	v_mov_b32_e32 v77, v239
	v_mov_b32_e32 v78, v240
	v_mov_b32_e32 v79, v241
	v_lshlrev_b32_e32 v80, 16, v76
	v_and_b32_e32 v81, 0xffff0000, v76
	v_lshlrev_b32_e32 v76, 16, v77
	v_and_b32_e32 v77, 0xffff0000, v77
	v_lshlrev_b32_e32 v82, 16, v78
	v_and_b32_e32 v83, 0xffff0000, v78
	v_lshlrev_b32_e32 v78, 16, v79
	v_and_b32_e32 v79, 0xffff0000, v79
	v_pk_mul_f32 v[72:73], v[72:73], v[76:77]
	v_pk_mul_f32 v[70:71], v[70:71], v[80:81]
	v_pk_mul_f32 v[76:77], v[68:69], v[78:79]
	v_pk_mul_f32 v[68:69], v[66:67], v[82:83]
	v_cvt_pk_bf16_f32 v66, v70, v71
	v_cvt_pk_bf16_f32 v67, v72, v73
	v_cvt_pk_bf16_f32 v68, v68, v69
	v_cvt_pk_bf16_f32 v69, v76, v77
	global_store_dwordx4 v[74:75], v[66:69], off offset:256
	s_nop 1
	v_add_co_u32_e32 v66, vcc, s50, v162
	s_nop 1
	v_addc_co_u32_e32 v67, vcc, 0, v163, vcc
	s_waitcnt vmcnt(15)
	v_mov_b32_e32 v68, v184
	v_mov_b32_e32 v69, v185
	v_mov_b32_e32 v70, v186
	v_mov_b32_e32 v71, v187
	v_lshlrev_b32_e32 v72, 16, v68
	v_and_b32_e32 v73, 0xffff0000, v68
	v_lshlrev_b32_e32 v74, 16, v70
	v_and_b32_e32 v75, 0xffff0000, v70
	v_lshlrev_b32_e32 v68, 16, v69
	v_and_b32_e32 v69, 0xffff0000, v69
	v_lshlrev_b32_e32 v70, 16, v71
	v_and_b32_e32 v71, 0xffff0000, v71
	v_pk_mul_f32 v[62:63], v[62:63], v[72:73]
	v_pk_mul_f32 v[58:59], v[58:59], v[74:75]
	v_pk_mul_f32 v[64:65], v[64:65], v[68:69]
	v_pk_mul_f32 v[68:69], v[60:61], v[70:71]
	v_cvt_pk_bf16_f32 v60, v62, v63
	v_cvt_pk_bf16_f32 v62, v58, v59
	v_add_co_u32_e32 v58, vcc, s50, v160
	v_cvt_pk_bf16_f32 v61, v64, v65
	v_cvt_pk_bf16_f32 v63, v68, v69
	v_addc_co_u32_e32 v59, vcc, 0, v161, vcc
	global_store_dwordx4 v[58:59], v[60:63], off
	s_waitcnt vmcnt(14)
; #define GAS __attribute__((address_space(1)))
; __device__ __forceinline__ u32x4 pack8(f32x4 v0, f32x4 v1) { u32x4 w; w.x = cvt_pk_bf16(v0[0], v0[1]); w.y = cvt_pk_bf16(v0[2], v0[3]); w.z = cvt_pk_bf16(v1[0], v1[1]); w.w = cvt_pk_bf16(v1[2], v1[3]); return w; }
; __device__ __forceinline__ void unpack8(u32x4 w, f32x4& v0, f32x4& v1) { v0 = (f32x4){bflo(w.x), bfhi(w.x), bflo(w.y), bfhi(w.y)}; v1 = (f32x4){bflo(w.z), bfhi(w.z), bflo(w.w), bfhi(w.w)}; }
; #define GAS __attribute__((address_space(1)))
;     __device__ __forceinline__ void operator()(const f32x4 (&acc)[2][2][4][2], const Unit& u, int wr, int wc, int fr, int fq) const {
;     ...
;             for (int m = 0; m < 4; ++m) { const size_t off = (size_t)(ai * HALF + m * 16) * 1024;
; #pragma unroll
;                 for (int bj = 0; bj < 2; ++bj) { f32x4 z0, z1; unpack8(*(const GAS u32x4*)(zb + off + bj * HALF), z0, z1);
;                     const f32x4 v0 = z0 * sigmoid4(acc[ai][bj][m][0] + bv[bj][0]), v1 = z1 * sigmoid4(acc[ai][bj][m][1] + bv[bj][1]);
;                     *(GAS u32x4*)(sob + off + bj * HALF) = pack8(v0, v1); } }
	v_mov_b32_e32 v60, v188
	v_mov_b32_e32 v61, v189
	v_mov_b32_e32 v62, v190
	v_mov_b32_e32 v63, v191
	v_lshlrev_b32_e32 v64, 16, v60
	v_and_b32_e32 v65, 0xffff0000, v60
	v_lshlrev_b32_e32 v60, 16, v61
	v_and_b32_e32 v61, 0xffff0000, v61
	v_lshlrev_b32_e32 v66, 16, v62
	v_and_b32_e32 v67, 0xffff0000, v62
	v_lshlrev_b32_e32 v62, 16, v63
	v_and_b32_e32 v63, 0xffff0000, v63
	v_pk_mul_f32 v[56:57], v[56:57], v[60:61]
	v_pk_mul_f32 v[54:55], v[54:55], v[64:65]
	v_pk_mul_f32 v[60:61], v[52:53], v[62:63]
	v_pk_mul_f32 v[52:53], v[50:51], v[66:67]
	v_cvt_pk_bf16_f32 v50, v54, v55
	v_cvt_pk_bf16_f32 v51, v56, v57
	v_cvt_pk_bf16_f32 v52, v52, v53
	v_cvt_pk_bf16_f32 v53, v60, v61
	global_store_dwordx4 v[58:59], v[50:53], off offset:256
	s_nop 1
	v_add_co_u32_e32 v50, vcc, s51, v162
	s_nop 1
	v_addc_co_u32_e32 v51, vcc, 0, v163, vcc
	s_waitcnt vmcnt(13)
	v_mov_b32_e32 v52, v192
	v_mov_b32_e32 v53, v193
	v_mov_b32_e32 v54, v194
	v_mov_b32_e32 v55, v195
	v_lshlrev_b32_e32 v56, 16, v52
	v_and_b32_e32 v57, 0xffff0000, v52
	v_lshlrev_b32_e32 v58, 16, v54
	v_and_b32_e32 v59, 0xffff0000, v54
	v_lshlrev_b32_e32 v52, 16, v53
	v_and_b32_e32 v53, 0xffff0000, v53
	v_lshlrev_b32_e32 v54, 16, v55
	v_and_b32_e32 v55, 0xffff0000, v55
	v_pk_mul_f32 v[46:47], v[46:47], v[56:57]
	v_pk_mul_f32 v[42:43], v[42:43], v[58:59]
	v_pk_mul_f32 v[48:49], v[48:49], v[52:53]
	v_pk_mul_f32 v[52:53], v[44:45], v[54:55]
	v_cvt_pk_bf16_f32 v44, v46, v47
	v_cvt_pk_bf16_f32 v46, v42, v43
	v_add_co_u32_e32 v42, vcc, s51, v160
	v_cvt_pk_bf16_f32 v45, v48, v49
	v_cvt_pk_bf16_f32 v47, v52, v53
	v_addc_co_u32_e32 v43, vcc, 0, v161, vcc
	global_store_dwordx4 v[42:43], v[44:47], off
	s_waitcnt vmcnt(12)
	v_mov_b32_e32 v44, v196
	v_mov_b32_e32 v45, v197
	v_mov_b32_e32 v46, v198
	v_mov_b32_e32 v47, v199
	v_lshlrev_b32_e32 v48, 16, v44
	v_and_b32_e32 v49, 0xffff0000, v44
	v_lshlrev_b32_e32 v44, 16, v45
	v_and_b32_e32 v45, 0xffff0000, v45
	v_lshlrev_b32_e32 v50, 16, v46
	v_and_b32_e32 v51, 0xffff0000, v46
	v_lshlrev_b32_e32 v46, 16, v47
	v_and_b32_e32 v47, 0xffff0000, v47
	v_pk_mul_f32 v[32:33], v[32:33], v[44:45]
	v_pk_mul_f32 v[30:31], v[30:31], v[48:49]
	v_pk_mul_f32 v[44:45], v[28:29], v[46:47]
	v_pk_mul_f32 v[28:29], v[26:27], v[50:51]
	v_cvt_pk_bf16_f32 v26, v30, v31
	v_cvt_pk_bf16_f32 v27, v32, v33
	v_cvt_pk_bf16_f32 v28, v28, v29
	v_cvt_pk_bf16_f32 v29, v44, v45
	global_store_dwordx4 v[42:43], v[26:29], off offset:256
	s_nop 1
	v_add_co_u32_e32 v26, vcc, s66, v162
	s_nop 1
	v_addc_co_u32_e32 v27, vcc, 0, v163, vcc
	s_waitcnt vmcnt(11)
	v_mov_b32_e32 v28, v200
	v_mov_b32_e32 v29, v201
	v_mov_b32_e32 v30, v202
	v_mov_b32_e32 v31, v203
	v_lshlrev_b32_e32 v32, 16, v28
	v_and_b32_e32 v33, 0xffff0000, v28
	v_lshlrev_b32_e32 v28, 16, v29
	v_and_b32_e32 v29, 0xffff0000, v29
	v_lshlrev_b32_e32 v42, 16, v30
	v_and_b32_e32 v43, 0xffff0000, v30
	v_lshlrev_b32_e32 v30, 16, v31
	v_and_b32_e32 v31, 0xffff0000, v31
	v_pk_mul_f32 v[18:19], v[18:19], v[32:33]
	v_pk_mul_f32 v[20:21], v[20:21], v[28:29]
	v_pk_mul_f32 v[28:29], v[12:13], v[30:31]
	v_pk_mul_f32 v[12:13], v[10:11], v[42:43]
	v_cvt_pk_bf16_f32 v10, v18, v19
	v_add_co_u32_e32 v18, vcc, s66, v160
	v_cvt_pk_bf16_f32 v11, v20, v21
	v_cvt_pk_bf16_f32 v12, v12, v13
	v_cvt_pk_bf16_f32 v13, v28, v29
	v_addc_co_u32_e32 v19, vcc, 0, v161, vcc
	global_store_dwordx4 v[18:19], v[10:13], off
	s_andn2_b64 vcc, exec, s[18:19]
	s_waitcnt vmcnt(10)
	v_mov_b32_e32 v10, v222
	v_mov_b32_e32 v11, v223
	v_mov_b32_e32 v12, v224
	v_mov_b32_e32 v13, v225
	v_lshlrev_b32_e32 v20, 16, v10
	v_and_b32_e32 v21, 0xffff0000, v10
	v_lshlrev_b32_e32 v10, 16, v11
	v_and_b32_e32 v11, 0xffff0000, v11
	v_lshlrev_b32_e32 v26, 16, v12
	v_and_b32_e32 v27, 0xffff0000, v12
	v_lshlrev_b32_e32 v12, 16, v13
	v_and_b32_e32 v13, 0xffff0000, v13
	v_pk_mul_f32 v[8:9], v[8:9], v[10:11]
	v_pk_mul_f32 v[6:7], v[6:7], v[20:21]
	v_pk_mul_f32 v[10:11], v[4:5], v[12:13]
	v_pk_mul_f32 v[4:5], v[2:3], v[26:27]
	v_cvt_pk_bf16_f32 v2, v6, v7
	v_cvt_pk_bf16_f32 v3, v8, v9
	v_cvt_pk_bf16_f32 v4, v4, v5
	v_cvt_pk_bf16_f32 v5, v10, v11
	global_store_dwordx4 v[18:19], v[2:5], off offset:256
	s_cbranch_vccnz .LBB0_923
	s_andn2_b64 vcc, exec, s[6:7]
	s_cbranch_vccnz .LBB0_922
	s_branch .LBB0_922

; #define GAS __attribute__((address_space(1)))
; __device__ __forceinline__ u32x4 pack8(f32x4 v0, f32x4 v1) { u32x4 w; w.x = cvt_pk_bf16(v0[0], v0[1]); w.y = cvt_pk_bf16(v0[2], v0[3]); w.z = cvt_pk_bf16(v1[0], v1[1]); w.w = cvt_pk_bf16(v1[2], v1[3]); return w; }
; __device__ __forceinline__ void unpack8(u32x4 w, f32x4& v0, f32x4& v1) { v0 = (f32x4){bflo(w.x), bfhi(w.x), bflo(w.y), bfhi(w.y)}; v1 = (f32x4){bflo(w.z), bfhi(w.z), bflo(w.w), bfhi(w.w)}; }
; #define PG8_BAR __builtin_amdgcn_s_barrier()
;     __device__ __forceinline__ void operator()(const f32x4 (&acc)[2][2][4][2], const Unit& u, int wr, int wc, int fr, int fq) const {
;         const int row0 = u.pm * BM + wr * 64 + fr, col0 = u.pn * BM + wc * 32 + 8 * fq;
;         const bool samp = u.pm >= 32;
;         GAS unsigned* flag = (GAS unsigned*)(flags + 64 * (u.pn * 4 + (u.pm & 3)));
;         if (MODE == 1 && samp) {
;             unsigned spins = 0u;
;             while (__hip_atomic_load(flag, __ATOMIC_RELAXED, __HIP_MEMORY_SCOPE_AGENT) < 8u) { __builtin_amdgcn_s_sleep(2); if (++spins > (1u << 18)) break; }
;             __builtin_amdgcn_fence(__ATOMIC_ACQUIRE, "agent"); asm volatile("s_waitcnt vmcnt(0)" ::: "memory");
;         }
; #pragma unroll
;         for (int ai = 0; ai < 2; ++ai)
; #pragma unroll
;             for (int m = 0; m < 4; ++m) { const size_t r = (size_t)(row0 + ai * HALF + m * 16); const size_t off = r * 2048 + col0; const bf16_t* gp = P + r * NPJ + 2560 + MODE * 2048 + col0;
; #pragma unroll
;                 for (int bj = 0; bj < 2; ++bj) { f32x4 g0, g1; unpack8(*(const GAS u32x4*)(gp + bj * HALF), g0, g1);
;                     f32x4 v0 = g0 * acc[ai][bj][m][0], v1 = g1 * acc[ai][bj][m][1];
;                     if (MODE == 1) { f32x4 t0, t1; unpack8(*(const GAS u32x4*)(T1 + off + bj * HALF), t0, t1); v0 += t0; v1 += t1; }
;                     const u32x4 w = pack8(v0, v1);
;                     if (MODE == 0 && samp) asm volatile("global_store_dwordx4 %0, %1, off sc1\n\ts_nop 1" :: "v"(O + off + bj * HALF), "v"(w) : "memory");
;                     else *(GAS u32x4*)(O + off + bj * HALF) = w; } }
; template <class Epi, class Sched, bool ALIGN_EPI = false, bool SP2 = false>
; __device__ __forceinline__ void gemm_phase(PG8_LAS unsigned char* lds, const Gemm g, const Sched& S, const Epi& E) {
;     ...
;         if constexpr (ALIGN_EPI) { if (wr == 0) PG8_BAR; }
.Lpx_1067:
	s_lshl_b32 s15, s91, 8
	v_or_b32_e32 v144, s15, v150
	v_lshl_add_u32 v146, s90, 8, v1
	v_ashrrev_i32_e32 v145, 31, v144
	v_mov_b64_e32 v[148:149], s[8:9]
	s_movk_i32 s95, 0x3400
	v_mad_i64_i32 v[148:149], s[0:1], v146, s95, v[148:149]
	v_lshlrev_b64 v[144:145], 1, v[144:145]
	v_lshl_add_u64 v[148:149], v[148:149], 0, v[144:145]
	s_movk_i32 s0, 0x1000
	v_add_co_u32_e32 v152, vcc, s0, v148
	s_cmp_gt_i32 s90, 31
	s_nop 0
	v_addc_co_u32_e32 v153, vcc, 0, v149, vcc
	global_load_dwordx4 v[222:225], v[152:153], off offset:1024
	global_load_dwordx4 v[226:229], v[152:153], off offset:1280
	v_add_co_u32_e32 v188, vcc, 0x34000, v152
	s_nop 1
	v_addc_co_u32_e32 v189, vcc, 0, v153, vcc
	global_load_dwordx4 v[230:233], v[188:189], off offset:1024
	global_load_dwordx4 v[234:237], v[188:189], off offset:1280
	v_add_co_u32_e32 v188, vcc, 0x68000, v152
	s_nop 1
	v_addc_co_u32_e32 v189, vcc, 0, v153, vcc
	global_load_dwordx4 v[238:241], v[188:189], off offset:1024
	global_load_dwordx4 v[242:245], v[188:189], off offset:1280
	v_add_co_u32_e32 v188, vcc, 0x9c000, v152
	s_nop 1
	v_addc_co_u32_e32 v189, vcc, 0, v153, vcc
	global_load_dwordx4 v[180:183], v[188:189], off offset:1024
	global_load_dwordx4 v[184:187], v[188:189], off offset:1280
	v_ashrrev_i32_e32 v147, 31, v146
	s_cselect_b64 s[52:53], -1, 0
	s_cmp_lt_i32 s90, 32
	s_cselect_b64 s[54:55], -1, 0
	s_mov_b64 s[42:43], -1
	s_and_b64 vcc, exec, s[12:13]
	s_cbranch_vccz .LBB0_1070
	s_barrier
.LBB0_1070:
	s_and_b64 vcc, exec, s[54:55]
	v_readlane_b32 s92, v254, 49
	s_mov_b64 s[2:3], 0x1400
	s_mov_b32 s93, 0x18000
	s_waitcnt vmcnt(7)
	s_nop 1
	v_mov_b32_e32 v152, v222
	v_mov_b32_e32 v153, v223
	v_mov_b32_e32 v154, v224
	v_mov_b32_e32 v155, v225
	v_lshlrev_b32_e32 v156, 16, v152
	v_and_b32_e32 v157, 0xffff0000, v152
	v_lshlrev_b32_e32 v152, 16, v153
	v_and_b32_e32 v153, 0xffff0000, v153
	v_lshlrev_b32_e32 v158, 16, v154
	v_and_b32_e32 v159, 0xffff0000, v154
	v_lshlrev_b32_e32 v154, 16, v155
	v_and_b32_e32 v155, 0xffff0000, v155
	v_pk_mul_f32 v[128:129], v[128:129], v[156:157]
	v_pk_mul_f32 v[130:131], v[130:131], v[152:153]
	v_pk_mul_f32 v[152:153], v[126:127], v[154:155]
	v_pk_mul_f32 v[126:127], v[124:125], v[158:159]
	v_cvt_pk_bf16_f32 v124, v128, v129
	v_lshlrev_b64 v[128:129], 12, v[146:147]
	v_lshl_add_u64 v[128:129], s[10:11], 0, v[128:129]
	v_cvt_pk_bf16_f32 v125, v130, v131
	v_cvt_pk_bf16_f32 v126, v126, v127
	v_cvt_pk_bf16_f32 v127, v152, v153
	v_lshl_add_u64 v[128:129], v[128:129], 0, v[144:145]
	s_cbranch_vccz .LBB0_1072
	global_store_dwordx4 v[128:129], v[124:127], off
	s_mov_b64 s[42:43], 0

; #define GAS __attribute__((address_space(1)))
; #define PG8_BAR __builtin_amdgcn_s_barrier()
; #define GAS __attribute__((address_space(1)))
;     __device__ __forceinline__ void operator()(const f32x4 (&acc)[2][2][4][2], const Unit& u, int wr, int wc, int fr, int fq) const {
;         const int row0 = u.pm * BM + wr * 64 + fr, col0 = u.pn * BM + wc * 32 + 8 * fq;
;         const bool samp = u.pm >= 32;
;         GAS unsigned* flag = (GAS unsigned*)(flags + 64 * (u.pn * 4 + (u.pm & 3)));
;         if (MODE == 1 && samp) {
;             unsigned spins = 0u;
;             while (__hip_atomic_load(flag, __ATOMIC_RELAXED, __HIP_MEMORY_SCOPE_AGENT) < 8u) { __builtin_amdgcn_s_sleep(2); if (++spins > (1u << 18)) break; }
;             __builtin_amdgcn_fence(__ATOMIC_ACQUIRE, "agent"); asm volatile("s_waitcnt vmcnt(0)" ::: "memory");
;         }
; template <class Epi, class Sched, bool ALIGN_EPI = false, bool SP2 = false>
; __device__ __forceinline__ void gemm_phase(PG8_LAS unsigned char* lds, const Gemm g, const Sched& S, const Epi& E) {
;     ...
;         if constexpr (ALIGN_EPI) { if (wr == 0) PG8_BAR; }
.Lpx_1157:
	s_lshl_b32 s19, s91, 8
	v_readlane_b32 s60, v251, 14
	s_and_b64 vcc, exec, s[16:17]
	s_cbranch_vccz .LBB0_1160
	s_barrier
.LBB0_1160:
	s_cmp_lt_i32 s90, 32
	v_readlane_b32 s92, v254, 49
	v_readlane_b32 s61, v251, 15
	v_readlane_b32 s62, v251, 16
	v_readlane_b32 s63, v251, 17
	v_readlane_b32 s64, v251, 18
	v_readlane_b32 s65, v251, 19
	v_readlane_b32 s66, v251, 20
	v_readlane_b32 s67, v251, 21
	s_mov_b32 s93, 0x18000
	s_mov_b32 s94, 0x8000
	s_movk_i32 s95, 0x3400
	s_cbranch_scc1 .LBB0_1178
	s_lshl_b32 s0, s90, 6
	s_and_b32 s0, s0, 0xc0
	s_or_b32 s0, s0, s19
	s_ashr_i32 s1, s0, 31
	s_lshl_b64 s[0:1], s[0:1], 2
	s_add_u32 s50, s30, s0
	s_addc_u32 s51, s31, s1
	s_mov_b32 s29, 0x40001
	s_branch .LBB0_1163

; #define GAS __attribute__((address_space(1)))
; __device__ __forceinline__ u32x4 pack8(f32x4 v0, f32x4 v1) { u32x4 w; w.x = cvt_pk_bf16(v0[0], v0[1]); w.y = cvt_pk_bf16(v0[2], v0[3]); w.z = cvt_pk_bf16(v1[0], v1[1]); w.w = cvt_pk_bf16(v1[2], v1[3]); return w; }
; #define PG8_BAR __builtin_amdgcn_s_barrier()
; #define GAS __attribute__((address_space(1)))
;     __device__ __forceinline__ void operator()(const f32x4 (&acc)[2][2][4][2], const Unit& u, int wr, int wc, int fr, int fq) const {
;         const int col0 = u.pn * BM + wc * 32 + 8 * fq;
;         const bool part = u.slab >= 0;
; #pragma unroll
;         for (int ai = 0; ai < 2; ++ai) {
;             const int rb = u.pm * BM + ai * HALF + wr * 64;
;             const int cb = rb < 8192 ? (rb >> 11) : 4 + ((rb - 8192) >> 6);
;             const float* g = gmod + (size_t)cb * 12288 + col0;
;             f32x4 gv[2][2];
; #pragma unroll
;             for (int bj = 0; bj < 2; ++bj)
; #pragma unroll
;                 for (int n = 0; n < 2; ++n) gv[bj][n] = *(const GAS f32x4*)(g + bj * HALF + 4 * n);
;             if (part) { bf16_t* base = SL + ((size_t)u.slab * 1024 + (size_t)(rb - 8192 + fr)) * 2048 + col0;
; #pragma unroll
;                 for (int m = 0; m < 4; ++m)
; #pragma unroll
;                     for (int bj = 0; bj < 2; ++bj) *(GAS u32x4*)(base + (size_t)(m * 16) * 2048 + bj * HALF) = pack8(gv[bj][0] * acc[ai][bj][m][0], gv[bj][1] * acc[ai][bj][m][1]);
;             } else { const size_t o0 = (size_t)(rb + fr) * 2048 + col0;
; #pragma unroll
;                 for (int m = 0; m < 4; ++m)
; #pragma unroll
;                     for (int bj = 0; bj < 2; ++bj) { const size_t o = o0 + (size_t)(m * 16) * 2048 + bj * HALF; f32x4 x0, x1; unpack8(*(const GAS u32x4*)(XB + o), x0, x1);
;                         const f32x4 v0 = x0 + gv[bj][0] * acc[ai][bj][m][0], v1 = x1 + gv[bj][1] * acc[ai][bj][m][1];
;                         if (OUTF != nullptr) { *(GAS f32x4*)(OUTF + o) = v0; *(GAS f32x4*)(OUTF + o + 4) = v1; } else *(GAS u32x4*)(XB + o) = pack8(v0, v1); }
; template <class Epi, class Sched, bool ALIGN_EPI = false, bool SP2 = false>
; __device__ __forceinline__ void gemm_phase(PG8_LAS unsigned char* lds, const Gemm g, const Sched& S, const Epi& E) {
;     ...
;         if constexpr (ALIGN_EPI) { if (wr == 0) PG8_BAR; }
.Lpx_1308:
	s_cmp_lt_i32 s78, 0
	s_cselect_b64 s[34:35], -1, 0
	s_lshl_b32 s11, s69, 8
	s_add_i32 s11, s11, s58
	s_add_i32 s13, s11, 0xffffe000
	s_lshr_b32 s1, s13, 6
	s_ashr_i32 s0, s11, 11
	s_add_i32 s1, s1, 4
	s_cmpk_lt_i32 s11, 0x2000
	s_cselect_b32 s0, s0, s1
	s_mul_hi_i32 s1, s0, 0xc000
	s_mul_i32 s0, s0, 0xc000
	v_lshl_or_b32 v164, s70, 8, v180
	s_add_u32 s0, s54, s0
	v_ashrrev_i32_e32 v165, 31, v164
	s_addc_u32 s1, s55, s1
	v_lshl_add_u64 v[136:137], v[164:165], 2, s[0:1]
	global_load_dwordx4 v[140:143], v[136:137], off offset:16
	global_load_dwordx4 v[144:147], v[136:137], off
	global_load_dwordx4 v[132:135], v[136:137], off offset:528
	s_nop 0
	global_load_dwordx4 v[136:139], v[136:137], off offset:512
	s_mov_b64 s[36:37], -1
	s_and_b64 vcc, exec, s[8:9]
	s_cbranch_vccz .LBB0_1311
	s_barrier
.LBB0_1311:
	s_and_b64 vcc, exec, s[34:35]
	s_cbranch_vccz .LBB0_1313
	v_or_b32_e32 v148, s11, v1
	v_ashrrev_i32_e32 v149, 31, v148
	v_lshlrev_b64 v[148:149], 12, v[148:149]
	v_lshl_add_u64 v[148:149], s[6:7], 0, v[148:149]
	v_lshl_add_u64 v[148:149], v[164:165], 1, v[148:149]
	global_load_dwordx4 v[222:225], v[148:149], off
	global_load_dwordx4 v[226:229], v[148:149], off offset:256
	v_add_co_u32_e32 v188, vcc, s73, v148
	s_nop 1
	v_addc_co_u32_e32 v189, vcc, 0, v149, vcc
	global_load_dwordx4 v[230:233], v[188:189], off
	global_load_dwordx4 v[234:237], v[188:189], off offset:256
	v_add_co_u32_e32 v188, vcc, s3, v148
	s_nop 1
	v_addc_co_u32_e32 v189, vcc, 0, v149, vcc
	global_load_dwordx4 v[238:241], v[188:189], off
	global_load_dwordx4 v[242:245], v[188:189], off offset:256
	v_add_co_u32_e32 v188, vcc, s46, v148
	s_nop 1
	v_addc_co_u32_e32 v189, vcc, 0, v149, vcc
	global_load_dwordx4 v[194:197], v[188:189], off
	global_load_dwordx4 v[198:201], v[188:189], off offset:256
	s_mov_b64 s[36:37], 0
	s_waitcnt vmcnt(7)
	s_nop 1
	v_mov_b32_e32 v182, v222
	v_mov_b32_e32 v183, v223
	v_mov_b32_e32 v184, v224
	v_mov_b32_e32 v185, v225
	v_lshlrev_b32_e32 v150, 16, v182
	v_and_b32_e32 v151, 0xffff0000, v182
	v_lshlrev_b32_e32 v166, 16, v183
	v_and_b32_e32 v167, 0xffff0000, v183
	v_lshlrev_b32_e32 v168, 16, v184
	v_and_b32_e32 v169, 0xffff0000, v184
	v_lshlrev_b32_e32 v172, 16, v185
	v_and_b32_e32 v173, 0xffff0000, v185
	v_pk_fma_f32 v[166:167], v[130:131], v[146:147], v[166:167]
	v_pk_fma_f32 v[150:151], v[128:129], v[144:145], v[150:151]
	v_pk_fma_f32 v[172:173], v[126:127], v[142:143], v[172:173]
	v_pk_fma_f32 v[168:169], v[124:125], v[140:141], v[168:169]
	v_cvt_pk_bf16_f32 v182, v150, v151
	v_cvt_pk_bf16_f32 v183, v166, v167
	v_cvt_pk_bf16_f32 v184, v168, v169
	v_cvt_pk_bf16_f32 v185, v172, v173
	global_store_dwordx4 v[148:149], v[182:185], off
	s_waitcnt vmcnt(7)
	s_nop 1
	v_mov_b32_e32 v182, v226
	v_mov_b32_e32 v183, v227
	v_mov_b32_e32 v184, v228
	v_mov_b32_e32 v185, v229
	v_lshlrev_b32_e32 v150, 16, v182
	v_and_b32_e32 v151, 0xffff0000, v182
	v_lshlrev_b32_e32 v166, 16, v183
	v_and_b32_e32 v167, 0xffff0000, v183
	v_lshlrev_b32_e32 v168, 16, v184
	v_and_b32_e32 v169, 0xffff0000, v184
	v_lshlrev_b32_e32 v172, 16, v185
	v_and_b32_e32 v173, 0xffff0000, v185
	v_pk_fma_f32 v[150:151], v[116:117], v[136:137], v[150:151]
	v_pk_fma_f32 v[166:167], v[118:119], v[138:139], v[166:167]
	v_pk_fma_f32 v[172:173], v[110:111], v[134:135], v[172:173]
	v_pk_fma_f32 v[168:169], v[108:109], v[132:133], v[168:169]
	v_cvt_pk_bf16_f32 v182, v150, v151
	v_add_co_u32_e32 v150, vcc, s73, v148
	v_cvt_pk_bf16_f32 v183, v166, v167
	v_cvt_pk_bf16_f32 v184, v168, v169
	v_cvt_pk_bf16_f32 v185, v172, v173
	v_addc_co_u32_e32 v151, vcc, 0, v149, vcc
	global_store_dwordx4 v[148:149], v[182:185], off offset:256
	s_waitcnt vmcnt(7)
	s_nop 1
	v_mov_b32_e32 v182, v230
	v_mov_b32_e32 v183, v231
	v_mov_b32_e32 v184, v232
	v_mov_b32_e32 v185, v233
	v_lshlrev_b32_e32 v166, 16, v182
	v_and_b32_e32 v167, 0xffff0000, v182
	v_lshlrev_b32_e32 v168, 16, v183
	v_and_b32_e32 v169, 0xffff0000, v183
	v_lshlrev_b32_e32 v172, 16, v184
	v_and_b32_e32 v173, 0xffff0000, v184
	v_lshlrev_b32_e32 v182, 16, v185
	v_and_b32_e32 v183, 0xffff0000, v185
	v_pk_fma_f32 v[168:169], v[122:123], v[146:147], v[168:169]
	v_pk_fma_f32 v[166:167], v[120:121], v[144:145], v[166:167]
	v_pk_fma_f32 v[186:187], v[114:115], v[142:143], v[182:183]
	v_pk_fma_f32 v[172:173], v[112:113], v[140:141], v[172:173]
	v_cvt_pk_bf16_f32 v182, v166, v167
	v_cvt_pk_bf16_f32 v183, v168, v169
	v_cvt_pk_bf16_f32 v184, v172, v173
	v_cvt_pk_bf16_f32 v185, v186, v187
	global_store_dwordx4 v[150:151], v[182:185], off
	s_waitcnt vmcnt(7)
; #define GAS __attribute__((address_space(1)))
; __device__ __forceinline__ u32x4 pack8(f32x4 v0, f32x4 v1) { u32x4 w; w.x = cvt_pk_bf16(v0[0], v0[1]); w.y = cvt_pk_bf16(v0[2], v0[3]); w.z = cvt_pk_bf16(v1[0], v1[1]); w.w = cvt_pk_bf16(v1[2], v1[3]); return w; }
; __device__ __forceinline__ void unpack8(u32x4 w, f32x4& v0, f32x4& v1) { v0 = (f32x4){bflo(w.x), bfhi(w.x), bflo(w.y), bfhi(w.y)}; v1 = (f32x4){bflo(w.z), bfhi(w.z), bflo(w.w), bfhi(w.w)}; }
; #define GAS __attribute__((address_space(1)))
;     __device__ __forceinline__ void operator()(const f32x4 (&acc)[2][2][4][2], const Unit& u, int wr, int wc, int fr, int fq) const {
;     ...
;             } else { const size_t o0 = (size_t)(rb + fr) * 2048 + col0;
; #pragma unroll
;                 for (int m = 0; m < 4; ++m)
; #pragma unroll
;                     for (int bj = 0; bj < 2; ++bj) { const size_t o = o0 + (size_t)(m * 16) * 2048 + bj * HALF; f32x4 x0, x1; unpack8(*(const GAS u32x4*)(XB + o), x0, x1);
;                         const f32x4 v0 = x0 + gv[bj][0] * acc[ai][bj][m][0], v1 = x1 + gv[bj][1] * acc[ai][bj][m][1];
;                         if (OUTF != nullptr) { *(GAS f32x4*)(OUTF + o) = v0; *(GAS f32x4*)(OUTF + o + 4) = v1; } else *(GAS u32x4*)(XB + o) = pack8(v0, v1); }
	s_nop 1
	v_mov_b32_e32 v182, v234
	v_mov_b32_e32 v183, v235
	v_mov_b32_e32 v184, v236
	v_mov_b32_e32 v185, v237
	v_lshlrev_b32_e32 v166, 16, v182
	v_and_b32_e32 v167, 0xffff0000, v182
	v_lshlrev_b32_e32 v168, 16, v183
	v_and_b32_e32 v169, 0xffff0000, v183
	v_lshlrev_b32_e32 v172, 16, v184
	v_and_b32_e32 v173, 0xffff0000, v184
	v_lshlrev_b32_e32 v182, 16, v185
	v_and_b32_e32 v183, 0xffff0000, v185
	v_pk_fma_f32 v[168:169], v[102:103], v[138:139], v[168:169]
	v_pk_fma_f32 v[166:167], v[100:101], v[136:137], v[166:167]
	v_pk_fma_f32 v[186:187], v[92:93], v[134:135], v[182:183]
	v_pk_fma_f32 v[172:173], v[90:91], v[132:133], v[172:173]
	v_cvt_pk_bf16_f32 v182, v166, v167
	v_cvt_pk_bf16_f32 v183, v168, v169
	v_cvt_pk_bf16_f32 v184, v172, v173
	v_cvt_pk_bf16_f32 v185, v186, v187
	global_store_dwordx4 v[150:151], v[182:185], off offset:256
	v_add_co_u32_e32 v150, vcc, s3, v148
	s_nop 1
	v_addc_co_u32_e32 v151, vcc, 0, v149, vcc
	s_waitcnt vmcnt(7)
	s_nop 1
	v_mov_b32_e32 v182, v238
	v_mov_b32_e32 v183, v239
	v_mov_b32_e32 v184, v240
	v_mov_b32_e32 v185, v241
	v_lshlrev_b32_e32 v166, 16, v182
	v_and_b32_e32 v167, 0xffff0000, v182
	v_lshlrev_b32_e32 v168, 16, v183
	v_and_b32_e32 v169, 0xffff0000, v183
	v_lshlrev_b32_e32 v172, 16, v184
	v_and_b32_e32 v173, 0xffff0000, v184
	v_lshlrev_b32_e32 v182, 16, v185
	v_and_b32_e32 v183, 0xffff0000, v185
	v_pk_fma_f32 v[168:169], v[106:107], v[146:147], v[168:169]
	v_pk_fma_f32 v[166:167], v[104:105], v[144:145], v[166:167]
	v_pk_fma_f32 v[186:187], v[96:97], v[142:143], v[182:183]
	v_pk_fma_f32 v[172:173], v[94:95], v[140:141], v[172:173]
	v_cvt_pk_bf16_f32 v182, v166, v167
	v_cvt_pk_bf16_f32 v183, v168, v169
	v_cvt_pk_bf16_f32 v184, v172, v173
	v_cvt_pk_bf16_f32 v185, v186, v187
	global_store_dwordx4 v[150:151], v[182:185], off
	s_waitcnt vmcnt(7)
	s_nop 1
	v_mov_b32_e32 v182, v242
	v_mov_b32_e32 v183, v243
	v_mov_b32_e32 v184, v244
	v_mov_b32_e32 v185, v245
	v_lshlrev_b32_e32 v166, 16, v182
	v_and_b32_e32 v167, 0xffff0000, v182
	v_lshlrev_b32_e32 v168, 16, v183
	v_and_b32_e32 v169, 0xffff0000, v183
	v_lshlrev_b32_e32 v172, 16, v184
	v_and_b32_e32 v173, 0xffff0000, v184
	v_lshlrev_b32_e32 v182, 16, v185
	v_and_b32_e32 v183, 0xffff0000, v185
	v_pk_fma_f32 v[166:167], v[82:83], v[136:137], v[166:167]
	v_pk_fma_f32 v[168:169], v[84:85], v[138:139], v[168:169]
	v_pk_fma_f32 v[186:187], v[76:77], v[134:135], v[182:183]
	v_pk_fma_f32 v[172:173], v[74:75], v[132:133], v[172:173]
	v_cvt_pk_bf16_f32 v182, v166, v167
	v_add_co_u32_e32 v166, vcc, s46, v148
	v_cvt_pk_bf16_f32 v183, v168, v169
	v_cvt_pk_bf16_f32 v184, v172, v173
	v_cvt_pk_bf16_f32 v185, v186, v187
	v_addc_co_u32_e32 v167, vcc, 0, v149, vcc
	global_store_dwordx4 v[150:151], v[182:185], off offset:256
	s_waitcnt vmcnt(7)
	s_nop 1
	v_mov_b32_e32 v148, v194
	v_mov_b32_e32 v149, v195
	v_mov_b32_e32 v150, v196
	v_mov_b32_e32 v151, v197
	v_lshlrev_b32_e32 v168, 16, v148
	v_and_b32_e32 v169, 0xffff0000, v148
	v_lshlrev_b32_e32 v148, 16, v149
	v_and_b32_e32 v149, 0xffff0000, v149
	v_lshlrev_b32_e32 v172, 16, v150
	v_and_b32_e32 v173, 0xffff0000, v150
	v_lshlrev_b32_e32 v150, 16, v151
	v_and_b32_e32 v151, 0xffff0000, v151
	v_pk_fma_f32 v[182:183], v[88:89], v[146:147], v[148:149]
	v_pk_fma_f32 v[148:149], v[86:87], v[144:145], v[168:169]
	v_pk_fma_f32 v[168:169], v[80:81], v[142:143], v[150:151]
	v_pk_fma_f32 v[150:151], v[78:79], v[140:141], v[172:173]
	v_cvt_pk_bf16_f32 v148, v148, v149
	v_cvt_pk_bf16_f32 v149, v182, v183
	v_cvt_pk_bf16_f32 v150, v150, v151
	v_cvt_pk_bf16_f32 v151, v168, v169
	global_store_dwordx4 v[166:167], v[148:151], off
	s_waitcnt vmcnt(7)
	s_nop 1
	v_mov_b32_e32 v148, v198
	v_mov_b32_e32 v149, v199
	v_mov_b32_e32 v150, v200
	v_mov_b32_e32 v151, v201
	v_lshlrev_b32_e32 v168, 16, v148
	v_and_b32_e32 v169, 0xffff0000, v148
	v_lshlrev_b32_e32 v148, 16, v149
	v_and_b32_e32 v149, 0xffff0000, v149
	v_lshlrev_b32_e32 v172, 16, v150
	v_and_b32_e32 v173, 0xffff0000, v150
	v_lshlrev_b32_e32 v150, 16, v151
	v_and_b32_e32 v151, 0xffff0000, v151
	v_pk_fma_f32 v[182:183], v[72:73], v[138:139], v[148:149]
	v_pk_fma_f32 v[148:149], v[70:71], v[136:137], v[168:169]
	v_pk_fma_f32 v[168:169], v[68:69], v[134:135], v[150:151]
	v_pk_fma_f32 v[150:151], v[66:67], v[132:133], v[172:173]
	v_cvt_pk_bf16_f32 v148, v148, v149
	v_cvt_pk_bf16_f32 v149, v182, v183
	v_cvt_pk_bf16_f32 v150, v150, v151
	v_cvt_pk_bf16_f32 v151, v168, v169
	global_store_dwordx4 v[166:167], v[148:151], off offset:256

; __device__ __forceinline__ u32x4 pack8(f32x4 v0, f32x4 v1) { u32x4 w; w.x = cvt_pk_bf16(v0[0], v0[1]); w.y = cvt_pk_bf16(v0[2], v0[3]); w.z = cvt_pk_bf16(v1[0], v1[1]); w.w = cvt_pk_bf16(v1[2], v1[3]); return w; }
; #define PG8_BAR __builtin_amdgcn_s_barrier()
;     __device__ __forceinline__ void operator()(const f32x4 (&acc)[2][2][4][2], const Unit& u, int wr, int wc, int fr, int fq) const {
;         const int row0 = u.pm * BM + wr * 64 + fr, col0 = u.pn * HALF + wc * 32 + 8 * fq;
;         bf16_t* const p0 = ACT + (size_t)row0 * 5632 + col0;
; #pragma unroll
;         for (int ai = 0; ai < 2; ++ai)
; #pragma unroll
;             for (int m = 0; m < 4; ++m) {
;                 const f32x4 g0 = acc[ai][0][m][0], g1 = acc[ai][0][m][1];
;                 const f32x4 v0 = g0 * sigmoid4(g0) * acc[ai][1][m][0], v1 = g1 * sigmoid4(g1) * acc[ai][1][m][1];
;                 store16_wt(p0 + (size_t)(ai * HALF + m * 16) * 5632, pack8(v0, v1)); }
; template <class Epi, class Sched, bool ALIGN_EPI = false, bool SP2 = false>
; __device__ __forceinline__ void gemm_phase(PG8_LAS unsigned char* lds, const Gemm g, const Sched& S, const Epi& E) {
;     ...
;         if constexpr (ALIGN_EPI) { if (wr == 0) PG8_BAR; }
.Lpx_1458:
	v_lshl_add_u32 v145, s70, 8, v1
	v_lshl_or_b32 v144, s69, 7, v148
	v_mov_b64_e32 v[146:147], s[8:9]
	s_movk_i32 s0, 0x2c00
	v_mad_i64_i32 v[146:147], s[0:1], v145, s0, v[146:147]
	v_ashrrev_i32_e32 v145, 31, v144
	v_lshl_add_u64 v[144:145], v[144:145], 1, v[146:147]
	s_and_b64 vcc, exec, s[10:11]
	s_cbranch_vccz .LBB0_1461
	s_barrier
.LBB0_1461:
	v_pk_mul_f32 v[146:147], v[128:129], s[74:75] op_sel_hi:[1,0]
	v_pk_mul_f32 v[150:151], v[130:131], s[74:75] op_sel_hi:[1,0]
	v_exp_f32_e32 v146, v146
	v_exp_f32_e32 v147, v147
	v_exp_f32_e32 v150, v150
	v_exp_f32_e32 v151, v151
	s_mov_b32 s0, 0x160000
	v_pk_add_f32 v[146:147], v[146:147], 1.0 op_sel_hi:[1,0]
	s_mov_b64 s[34:35], -1
	v_pk_add_f32 v[150:151], v[150:151], 1.0 op_sel_hi:[1,0]
	v_rcp_f32_e32 v146, v146
	v_rcp_f32_e32 v147, v147
	v_rcp_f32_e32 v150, v150
	v_rcp_f32_e32 v151, v151
	v_pk_mul_f32 v[128:129], v[128:129], v[146:147]
	s_nop 0
	v_pk_mul_f32 v[124:125], v[124:125], v[128:129]
	v_pk_mul_f32 v[130:131], v[130:131], v[150:151]
	v_pk_mul_f32 v[128:129], v[120:121], s[74:75] op_sel_hi:[1,0]
	v_pk_mul_f32 v[126:127], v[126:127], v[130:131]
	v_pk_mul_f32 v[130:131], v[122:123], s[74:75] op_sel_hi:[1,0]
	v_exp_f32_e32 v128, v128
	v_exp_f32_e32 v129, v129
	v_exp_f32_e32 v130, v130
	v_exp_f32_e32 v131, v131
	v_pk_add_f32 v[128:129], v[128:129], 1.0 op_sel_hi:[1,0]
	s_nop 0
	v_rcp_f32_e32 v128, v128
	v_pk_add_f32 v[130:131], v[130:131], 1.0 op_sel_hi:[1,0]
	v_rcp_f32_e32 v129, v129
	v_rcp_f32_e32 v130, v130
	v_rcp_f32_e32 v131, v131
	v_pk_mul_f32 v[120:121], v[120:121], v[128:129]
	v_pk_mul_f32 v[122:123], v[122:123], v[130:131]
	s_nop 0
	v_pk_mul_f32 v[122:123], v[118:119], v[122:123]
	v_pk_mul_f32 v[118:119], v[116:117], v[120:121]
	v_cvt_pk_bf16_f32 v116, v124, v125
	v_cvt_pk_bf16_f32 v117, v126, v127
	v_cvt_pk_bf16_f32 v118, v118, v119
	v_cvt_pk_bf16_f32 v119, v122, v123
	global_store_dwordx4 v[144:145], v[116:119], off sc1
	s_nop 1
	v_pk_mul_f32 v[116:117], v[112:113], s[74:75] op_sel_hi:[1,0]
	v_pk_mul_f32 v[118:119], v[114:115], s[74:75] op_sel_hi:[1,0]
	v_exp_f32_e32 v116, v116
	v_exp_f32_e32 v117, v117
	v_exp_f32_e32 v118, v118
	v_exp_f32_e32 v119, v119
	v_pk_add_f32 v[116:117], v[116:117], 1.0 op_sel_hi:[1,0]
	s_nop 0
	v_rcp_f32_e32 v116, v116
	v_pk_add_f32 v[118:119], v[118:119], 1.0 op_sel_hi:[1,0]
	v_rcp_f32_e32 v117, v117
	v_rcp_f32_e32 v118, v118
	v_rcp_f32_e32 v119, v119
	v_pk_mul_f32 v[112:113], v[112:113], v[116:117]
	s_nop 0
	v_pk_mul_f32 v[108:109], v[108:109], v[112:113]
	v_pk_mul_f32 v[114:115], v[114:115], v[118:119]
	v_pk_mul_f32 v[112:113], v[104:105], s[74:75] op_sel_hi:[1,0]
	v_pk_mul_f32 v[110:111], v[110:111], v[114:115]
	v_pk_mul_f32 v[114:115], v[106:107], s[74:75] op_sel_hi:[1,0]
	v_exp_f32_e32 v112, v112
	v_exp_f32_e32 v113, v113
	v_exp_f32_e32 v114, v114
	v_exp_f32_e32 v115, v115
	v_pk_add_f32 v[112:113], v[112:113], 1.0 op_sel_hi:[1,0]
	s_nop 0
	v_rcp_f32_e32 v112, v112
	v_pk_add_f32 v[114:115], v[114:115], 1.0 op_sel_hi:[1,0]
	v_rcp_f32_e32 v113, v113
	v_rcp_f32_e32 v114, v114
	v_rcp_f32_e32 v115, v115
	v_pk_mul_f32 v[104:105], v[104:105], v[112:113]
	v_pk_mul_f32 v[106:107], v[106:107], v[114:115]
	s_nop 0
	v_pk_mul_f32 v[106:107], v[102:103], v[106:107]
	v_pk_mul_f32 v[102:103], v[100:101], v[104:105]
	v_add_co_u32_e32 v104, vcc, s65, v144
	v_cvt_pk_bf16_f32 v100, v108, v109
	v_cvt_pk_bf16_f32 v101, v110, v111
	v_cvt_pk_bf16_f32 v102, v102, v103
	v_cvt_pk_bf16_f32 v103, v106, v107
	v_addc_co_u32_e32 v105, vcc, 0, v145, vcc
	global_store_dwordx4 v[104:105], v[100:103], off sc1
	s_nop 1
	v_pk_mul_f32 v[100:101], v[94:95], s[74:75] op_sel_hi:[1,0]
	v_pk_mul_f32 v[102:103], v[96:97], s[74:75] op_sel_hi:[1,0]
	v_exp_f32_e32 v100, v100
	v_exp_f32_e32 v101, v101
	v_exp_f32_e32 v102, v102
	v_exp_f32_e32 v103, v103
	v_pk_add_f32 v[100:101], v[100:101], 1.0 op_sel_hi:[1,0]
	s_nop 0
	v_rcp_f32_e32 v100, v100
	v_pk_add_f32 v[102:103], v[102:103], 1.0 op_sel_hi:[1,0]
	v_rcp_f32_e32 v101, v101
	v_rcp_f32_e32 v102, v102
	v_rcp_f32_e32 v103, v103
	v_pk_mul_f32 v[94:95], v[94:95], v[100:101]
	s_nop 0
	v_pk_mul_f32 v[90:91], v[90:91], v[94:95]
	v_pk_mul_f32 v[96:97], v[96:97], v[102:103]
	v_pk_mul_f32 v[94:95], v[86:87], s[74:75] op_sel_hi:[1,0]
	v_pk_mul_f32 v[92:93], v[92:93], v[96:97]
	v_pk_mul_f32 v[96:97], v[88:89], s[74:75] op_sel_hi:[1,0]
	v_exp_f32_e32 v94, v94
	v_exp_f32_e32 v95, v95
	v_exp_f32_e32 v96, v96
	v_exp_f32_e32 v97, v97
	v_pk_add_f32 v[94:95], v[94:95], 1.0 op_sel_hi:[1,0]
	s_nop 0
	v_rcp_f32_e32 v94, v94
	v_pk_add_f32 v[96:97], v[96:97], 1.0 op_sel_hi:[1,0]
	v_rcp_f32_e32 v95, v95
	v_rcp_f32_e32 v96, v96
	v_rcp_f32_e32 v97, v97
	v_pk_mul_f32 v[86:87], v[86:87], v[94:95]
	v_pk_mul_f32 v[88:89], v[88:89], v[96:97]
	s_nop 0
	v_pk_mul_f32 v[88:89], v[84:85], v[88:89]
	v_pk_mul_f32 v[84:85], v[82:83], v[86:87]
	v_add_co_u32_e32 v86, vcc, s64, v144
	v_cvt_pk_bf16_f32 v82, v90, v91
	v_cvt_pk_bf16_f32 v83, v92, v93
	v_cvt_pk_bf16_f32 v84, v84, v85
	v_cvt_pk_bf16_f32 v85, v88, v89
	v_addc_co_u32_e32 v87, vcc, 0, v145, vcc
	global_store_dwordx4 v[86:87], v[82:85], off sc1
	s_nop 1
	v_pk_mul_f32 v[82:83], v[78:79], s[74:75] op_sel_hi:[1,0]
	v_pk_mul_f32 v[84:85], v[80:81], s[74:75] op_sel_hi:[1,0]
	v_exp_f32_e32 v82, v82
	v_exp_f32_e32 v83, v83
	v_exp_f32_e32 v84, v84
	v_exp_f32_e32 v85, v85
	v_pk_add_f32 v[82:83], v[82:83], 1.0 op_sel_hi:[1,0]
	s_nop 0
	v_rcp_f32_e32 v82, v82
	v_pk_add_f32 v[84:85], v[84:85], 1.0 op_sel_hi:[1,0]
	v_rcp_f32_e32 v83, v83
	v_rcp_f32_e32 v84, v84
	v_rcp_f32_e32 v85, v85
	v_pk_mul_f32 v[78:79], v[78:79], v[82:83]
	s_nop 0
	v_pk_mul_f32 v[74:75], v[74:75], v[78:79]
	v_pk_mul_f32 v[80:81], v[80:81], v[84:85]
; __device__ __forceinline__ u32x4 pack8(f32x4 v0, f32x4 v1) { u32x4 w; w.x = cvt_pk_bf16(v0[0], v0[1]); w.y = cvt_pk_bf16(v0[2], v0[3]); w.z = cvt_pk_bf16(v1[0], v1[1]); w.w = cvt_pk_bf16(v1[2], v1[3]); return w; }
;     __device__ __forceinline__ void operator()(const f32x4 (&acc)[2][2][4][2], const Unit& u, int wr, int wc, int fr, int fq) const {
;     ...
; #pragma unroll
;         for (int ai = 0; ai < 2; ++ai)
; #pragma unroll
;             for (int m = 0; m < 4; ++m) {
;                 const f32x4 g0 = acc[ai][0][m][0], g1 = acc[ai][0][m][1];
;                 const f32x4 v0 = g0 * sigmoid4(g0) * acc[ai][1][m][0], v1 = g1 * sigmoid4(g1) * acc[ai][1][m][1];
;                 store16_wt(p0 + (size_t)(ai * HALF + m * 16) * 5632, pack8(v0, v1)); }
	v_pk_mul_f32 v[78:79], v[70:71], s[74:75] op_sel_hi:[1,0]
	v_pk_mul_f32 v[76:77], v[76:77], v[80:81]
	v_pk_mul_f32 v[80:81], v[72:73], s[74:75] op_sel_hi:[1,0]
	v_exp_f32_e32 v78, v78
	v_exp_f32_e32 v79, v79
	v_exp_f32_e32 v80, v80
	v_exp_f32_e32 v81, v81
	v_pk_add_f32 v[78:79], v[78:79], 1.0 op_sel_hi:[1,0]
	s_nop 0
	v_rcp_f32_e32 v78, v78
	v_pk_add_f32 v[80:81], v[80:81], 1.0 op_sel_hi:[1,0]
	v_rcp_f32_e32 v79, v79
	v_rcp_f32_e32 v80, v80
	v_rcp_f32_e32 v81, v81
	v_pk_mul_f32 v[70:71], v[70:71], v[78:79]
	v_pk_mul_f32 v[72:73], v[72:73], v[80:81]
	s_nop 0
	v_pk_mul_f32 v[72:73], v[68:69], v[72:73]
	v_pk_mul_f32 v[68:69], v[66:67], v[70:71]
	v_add_co_u32_e32 v70, vcc, s66, v144
	v_cvt_pk_bf16_f32 v66, v74, v75
	v_cvt_pk_bf16_f32 v67, v76, v77
	v_cvt_pk_bf16_f32 v68, v68, v69
	v_cvt_pk_bf16_f32 v69, v72, v73
	v_addc_co_u32_e32 v71, vcc, 0, v145, vcc
	global_store_dwordx4 v[70:71], v[66:69], off sc1
	s_nop 1
	v_pk_mul_f32 v[66:67], v[62:63], s[74:75] op_sel_hi:[1,0]
	v_pk_mul_f32 v[68:69], v[64:65], s[74:75] op_sel_hi:[1,0]
	v_exp_f32_e32 v66, v66
	v_exp_f32_e32 v67, v67
	v_exp_f32_e32 v68, v68
	v_exp_f32_e32 v69, v69
	v_pk_add_f32 v[66:67], v[66:67], 1.0 op_sel_hi:[1,0]
	s_nop 0
	v_rcp_f32_e32 v66, v66
	v_pk_add_f32 v[68:69], v[68:69], 1.0 op_sel_hi:[1,0]
	v_rcp_f32_e32 v67, v67
	v_rcp_f32_e32 v68, v68
	v_rcp_f32_e32 v69, v69
	v_pk_mul_f32 v[62:63], v[62:63], v[66:67]
	s_nop 0
	v_pk_mul_f32 v[58:59], v[58:59], v[62:63]
	v_pk_mul_f32 v[64:65], v[64:65], v[68:69]
	v_pk_mul_f32 v[62:63], v[54:55], s[74:75] op_sel_hi:[1,0]
	v_pk_mul_f32 v[60:61], v[60:61], v[64:65]
	v_pk_mul_f32 v[64:65], v[56:57], s[74:75] op_sel_hi:[1,0]
	v_exp_f32_e32 v62, v62
	v_exp_f32_e32 v63, v63
	v_exp_f32_e32 v64, v64
	v_exp_f32_e32 v65, v65
	v_pk_add_f32 v[62:63], v[62:63], 1.0 op_sel_hi:[1,0]
	s_nop 0
	v_rcp_f32_e32 v62, v62
	v_pk_add_f32 v[64:65], v[64:65], 1.0 op_sel_hi:[1,0]
	v_rcp_f32_e32 v63, v63
	v_rcp_f32_e32 v64, v64
	v_rcp_f32_e32 v65, v65
	v_pk_mul_f32 v[54:55], v[54:55], v[62:63]
	v_pk_mul_f32 v[56:57], v[56:57], v[64:65]
	s_nop 0
	v_pk_mul_f32 v[56:57], v[52:53], v[56:57]
	v_pk_mul_f32 v[52:53], v[50:51], v[54:55]
	v_add_co_u32_e32 v54, vcc, s0, v144
	v_cvt_pk_bf16_f32 v50, v58, v59
	v_cvt_pk_bf16_f32 v51, v60, v61
	v_cvt_pk_bf16_f32 v52, v52, v53
	v_cvt_pk_bf16_f32 v53, v56, v57
	v_addc_co_u32_e32 v55, vcc, 0, v145, vcc
	global_store_dwordx4 v[54:55], v[50:53], off sc1
	s_mov_b32 s0, 0x18c000
	s_nop 0
	v_pk_mul_f32 v[50:51], v[46:47], s[74:75] op_sel_hi:[1,0]
	v_pk_mul_f32 v[52:53], v[48:49], s[74:75] op_sel_hi:[1,0]
	v_exp_f32_e32 v50, v50
	v_exp_f32_e32 v51, v51
	v_exp_f32_e32 v52, v52
	v_exp_f32_e32 v53, v53
	v_pk_add_f32 v[50:51], v[50:51], 1.0 op_sel_hi:[1,0]
	s_nop 0
	v_rcp_f32_e32 v50, v50
	v_pk_add_f32 v[52:53], v[52:53], 1.0 op_sel_hi:[1,0]
	v_rcp_f32_e32 v51, v51
	v_rcp_f32_e32 v52, v52
	v_rcp_f32_e32 v53, v53
	v_pk_mul_f32 v[46:47], v[46:47], v[50:51]
	s_nop 0
	v_pk_mul_f32 v[42:43], v[42:43], v[46:47]
	v_pk_mul_f32 v[48:49], v[48:49], v[52:53]
	v_pk_mul_f32 v[46:47], v[38:39], s[74:75] op_sel_hi:[1,0]
	v_pk_mul_f32 v[44:45], v[44:45], v[48:49]
	v_pk_mul_f32 v[48:49], v[40:41], s[74:75] op_sel_hi:[1,0]
	v_exp_f32_e32 v46, v46
	v_exp_f32_e32 v47, v47
	v_exp_f32_e32 v48, v48
	v_exp_f32_e32 v49, v49
	v_pk_add_f32 v[46:47], v[46:47], 1.0 op_sel_hi:[1,0]
	s_nop 0
	v_rcp_f32_e32 v46, v46
	v_pk_add_f32 v[48:49], v[48:49], 1.0 op_sel_hi:[1,0]
	v_rcp_f32_e32 v47, v47
	v_rcp_f32_e32 v48, v48
	v_rcp_f32_e32 v49, v49
	v_pk_mul_f32 v[38:39], v[38:39], v[46:47]
	v_pk_mul_f32 v[40:41], v[40:41], v[48:49]
	s_nop 0
	v_pk_mul_f32 v[40:41], v[36:37], v[40:41]
	v_pk_mul_f32 v[36:37], v[34:35], v[38:39]
	v_add_co_u32_e32 v38, vcc, s0, v144
	v_cvt_pk_bf16_f32 v34, v42, v43
	v_cvt_pk_bf16_f32 v35, v44, v45
	v_cvt_pk_bf16_f32 v36, v36, v37
	v_cvt_pk_bf16_f32 v37, v40, v41
	v_addc_co_u32_e32 v39, vcc, 0, v145, vcc
	global_store_dwordx4 v[38:39], v[34:37], off sc1
	s_mov_b32 s0, 0x1b8000
	s_nop 0
	v_pk_mul_f32 v[34:35], v[30:31], s[74:75] op_sel_hi:[1,0]
	v_pk_mul_f32 v[36:37], v[32:33], s[74:75] op_sel_hi:[1,0]
	v_exp_f32_e32 v34, v34
	v_exp_f32_e32 v35, v35
	v_exp_f32_e32 v36, v36
	v_exp_f32_e32 v37, v37
	v_pk_add_f32 v[34:35], v[34:35], 1.0 op_sel_hi:[1,0]
	s_nop 0
	v_rcp_f32_e32 v34, v34
	v_pk_add_f32 v[36:37], v[36:37], 1.0 op_sel_hi:[1,0]
	v_rcp_f32_e32 v35, v35
	v_rcp_f32_e32 v36, v36
	v_rcp_f32_e32 v37, v37
	v_pk_mul_f32 v[30:31], v[30:31], v[34:35]
	s_nop 0
	v_pk_mul_f32 v[26:27], v[26:27], v[30:31]
	v_pk_mul_f32 v[32:33], v[32:33], v[36:37]
	v_pk_mul_f32 v[30:31], v[22:23], s[74:75] op_sel_hi:[1,0]
	v_pk_mul_f32 v[28:29], v[28:29], v[32:33]
	v_pk_mul_f32 v[32:33], v[24:25], s[74:75] op_sel_hi:[1,0]
	v_exp_f32_e32 v30, v30
	v_exp_f32_e32 v31, v31
	v_exp_f32_e32 v32, v32
	v_exp_f32_e32 v33, v33
	v_pk_add_f32 v[30:31], v[30:31], 1.0 op_sel_hi:[1,0]
	s_nop 0
	v_rcp_f32_e32 v30, v30
	v_pk_add_f32 v[32:33], v[32:33], 1.0 op_sel_hi:[1,0]
	v_rcp_f32_e32 v31, v31
	v_rcp_f32_e32 v32, v32
	v_rcp_f32_e32 v33, v33
	v_pk_mul_f32 v[22:23], v[22:23], v[30:31]
	v_pk_mul_f32 v[24:25], v[24:25], v[32:33]
	s_nop 0
	v_pk_mul_f32 v[24:25], v[20:21], v[24:25]
	v_pk_mul_f32 v[20:21], v[18:19], v[22:23]
	v_add_co_u32_e32 v22, vcc, s0, v144
	v_cvt_pk_bf16_f32 v18, v26, v27
	v_cvt_pk_bf16_f32 v19, v28, v29
	v_cvt_pk_bf16_f32 v20, v20, v21
	v_cvt_pk_bf16_f32 v21, v24, v25
	v_addc_co_u32_e32 v23, vcc, 0, v145, vcc
	global_store_dwordx4 v[22:23], v[18:21], off sc1
	s_nop 1
	v_pk_mul_f32 v[18:19], v[14:15], s[74:75] op_sel_hi:[1,0]
	v_pk_mul_f32 v[20:21], v[16:17], s[74:75] op_sel_hi:[1,0]
	v_exp_f32_e32 v18, v18
	v_exp_f32_e32 v19, v19
	v_exp_f32_e32 v20, v20
	v_exp_f32_e32 v21, v21
	v_pk_add_f32 v[18:19], v[18:19], 1.0 op_sel_hi:[1,0]
	s_nop 0
	v_rcp_f32_e32 v18, v18
	v_pk_add_f32 v[20:21], v[20:21], 1.0 op_sel_hi:[1,0]
	v_rcp_f32_e32 v19, v19
	v_rcp_f32_e32 v20, v20
	v_rcp_f32_e32 v21, v21
	v_pk_mul_f32 v[14:15], v[14:15], v[18:19]
	s_nop 0
	v_pk_mul_f32 v[10:11], v[10:11], v[14:15]
	v_pk_mul_f32 v[16:17], v[16:17], v[20:21]
	v_pk_mul_f32 v[14:15], v[6:7], s[74:75] op_sel_hi:[1,0]
	v_pk_mul_f32 v[12:13], v[12:13], v[16:17]
	v_pk_mul_f32 v[16:17], v[8:9], s[74:75] op_sel_hi:[1,0]
	v_exp_f32_e32 v14, v14
	v_exp_f32_e32 v15, v15
	v_exp_f32_e32 v16, v16
	v_exp_f32_e32 v17, v17
	v_pk_add_f32 v[14:15], v[14:15], 1.0 op_sel_hi:[1,0]
	s_nop 0
	v_rcp_f32_e32 v14, v14
	v_pk_add_f32 v[16:17], v[16:17], 1.0 op_sel_hi:[1,0]
	v_rcp_f32_e32 v15, v15
	v_rcp_f32_e32 v16, v16
	v_rcp_f32_e32 v17, v17
	v_pk_mul_f32 v[6:7], v[6:7], v[14:15]
	v_pk_mul_f32 v[8:9], v[8:9], v[16:17]
	s_nop 0
	v_pk_mul_f32 v[8:9], v[4:5], v[8:9]
	v_pk_mul_f32 v[4:5], v[2:3], v[6:7]
	v_add_co_u32_e32 v6, vcc, 0x1e4000, v144
	v_cvt_pk_bf16_f32 v2, v10, v11
	s_nop 0
	v_addc_co_u32_e32 v7, vcc, 0, v145, vcc
	v_cvt_pk_bf16_f32 v3, v12, v13
	v_cvt_pk_bf16_f32 v4, v4, v5
	v_cvt_pk_bf16_f32 v5, v8, v9
	s_andn2_b64 vcc, exec, s[38:39]
	global_store_dwordx4 v[6:7], v[2:5], off sc1
	s_cbranch_vccnz .LBB0_1454
	s_andn2_b64 vcc, exec, s[6:7]
	s_cbranch_vccnz .LBB0_1453
	s_branch .LBB0_1453

; #define GAS __attribute__((address_space(1)))
; __device__ __forceinline__ u32x4 pack8(f32x4 v0, f32x4 v1) { u32x4 w; w.x = cvt_pk_bf16(v0[0], v0[1]); w.y = cvt_pk_bf16(v0[2], v0[3]); w.z = cvt_pk_bf16(v1[0], v1[1]); w.w = cvt_pk_bf16(v1[2], v1[3]); return w; }
; #define PG8_BAR __builtin_amdgcn_s_barrier()
; #define GAS __attribute__((address_space(1)))
;     __device__ __forceinline__ void operator()(const f32x4 (&acc)[2][2][4][2], const Unit& u, int wr, int wc, int fr, int fq) const {
;         const int col0 = u.pn * BM + wc * 32 + 8 * fq;
;         const bool part = u.slab >= 0;
; #pragma unroll
;         for (int ai = 0; ai < 2; ++ai) {
;             const int rb = u.pm * BM + ai * HALF + wr * 64;
;             const int cb = rb < 8192 ? (rb >> 11) : 4 + ((rb - 8192) >> 6);
;             const float* g = gmod + (size_t)cb * 12288 + col0;
;             f32x4 gv[2][2];
; #pragma unroll
;             for (int bj = 0; bj < 2; ++bj)
; #pragma unroll
;                 for (int n = 0; n < 2; ++n) gv[bj][n] = *(const GAS f32x4*)(g + bj * HALF + 4 * n);
;             if (part) { bf16_t* base = SL + ((size_t)u.slab * 1024 + (size_t)(rb - 8192 + fr)) * 2048 + col0;
; #pragma unroll
;                 for (int m = 0; m < 4; ++m)
; #pragma unroll
;                     for (int bj = 0; bj < 2; ++bj) *(GAS u32x4*)(base + (size_t)(m * 16) * 2048 + bj * HALF) = pack8(gv[bj][0] * acc[ai][bj][m][0], gv[bj][1] * acc[ai][bj][m][1]);
;             } else { const size_t o0 = (size_t)(rb + fr) * 2048 + col0;
; #pragma unroll
;                 for (int m = 0; m < 4; ++m)
; #pragma unroll
;                     for (int bj = 0; bj < 2; ++bj) { const size_t o = o0 + (size_t)(m * 16) * 2048 + bj * HALF; f32x4 x0, x1; unpack8(*(const GAS u32x4*)(XB + o), x0, x1);
;                         const f32x4 v0 = x0 + gv[bj][0] * acc[ai][bj][m][0], v1 = x1 + gv[bj][1] * acc[ai][bj][m][1];
;                         if (OUTF != nullptr) { *(GAS f32x4*)(OUTF + o) = v0; *(GAS f32x4*)(OUTF + o + 4) = v1; } else *(GAS u32x4*)(XB + o) = pack8(v0, v1); }
; template <class Epi, class Sched, bool ALIGN_EPI = false, bool SP2 = false>
; __device__ __forceinline__ void gemm_phase(PG8_LAS unsigned char* lds, const Gemm g, const Sched& S, const Epi& E) {
;     ...
;         if constexpr (ALIGN_EPI) { if (wr == 0) PG8_BAR; }
.Lpx_1654:
	s_cmp_lt_i32 s78, 0
	s_cselect_b64 s[34:35], -1, 0
	s_lshl_b32 s15, s71, 8
	s_add_i32 s15, s15, s59
	s_add_i32 s42, s15, 0xffffe000
	s_lshr_b32 s1, s42, 6
	s_ashr_i32 s0, s15, 11
	s_add_i32 s1, s1, 4
	s_cmpk_lt_i32 s15, 0x2000
	s_cselect_b32 s0, s0, s1
	s_mul_hi_i32 s1, s0, 0xc000
	s_mul_i32 s0, s0, 0xc000
	v_lshl_or_b32 v180, s75, 8, v188
	s_add_u32 s0, s55, s0
	v_ashrrev_i32_e32 v181, 31, v180
	s_addc_u32 s1, s56, s1
	v_lshl_add_u64 v[136:137], v[180:181], 2, s[0:1]
	global_load_dwordx4 v[140:143], v[136:137], off offset:16
	global_load_dwordx4 v[144:147], v[136:137], off
	global_load_dwordx4 v[132:135], v[136:137], off offset:528
	s_nop 0
	global_load_dwordx4 v[136:139], v[136:137], off offset:512
	s_and_b64 vcc, exec, s[12:13]
	s_cbranch_vccz .LBB0_1657
	s_barrier
.LBB0_1657:
	v_cndmask_b32_e64 v148, 0, 1, s[8:9]
	s_mov_b64 s[40:41], -1
	s_and_b64 vcc, exec, s[34:35]
	v_cmp_ne_u32_e64 s[38:39], 1, v148
	s_cbranch_vccz .LBB0_1684
	v_or_b32_e32 v148, s15, v1
	v_ashrrev_i32_e32 v149, 31, v148
	v_lshlrev_b64 v[148:149], 11, v[148:149]
	v_lshl_add_u64 v[186:187], v[148:149], 0, v[180:181]
	v_lshl_add_u64 v[182:183], v[186:187], 1, s[10:11]
	global_load_dwordx4 v[222:225], v[182:183], off
	global_load_dwordx4 v[226:229], v[182:183], off offset:256
	v_add_co_u32_e32 v198, vcc, 0x10000, v182
	s_nop 1
	v_addc_co_u32_e32 v199, vcc, 0, v183, vcc
	global_load_dwordx4 v[230:233], v[198:199], off
	global_load_dwordx4 v[234:237], v[198:199], off offset:256
	v_add_co_u32_e32 v198, vcc, 0x20000, v182
	s_nop 1
	v_addc_co_u32_e32 v199, vcc, 0, v183, vcc
	global_load_dwordx4 v[238:241], v[198:199], off
	global_load_dwordx4 v[242:245], v[198:199], off offset:256
	v_add_co_u32_e32 v198, vcc, 0x30000, v182
	s_nop 1
	v_addc_co_u32_e32 v199, vcc, 0, v183, vcc
	global_load_dwordx4 v[190:193], v[198:199], off
	global_load_dwordx4 v[194:197], v[198:199], off offset:256
	s_and_b64 vcc, exec, s[38:39]
	v_lshl_add_u64 v[184:185], v[186:187], 2, s[6:7]
	s_waitcnt vmcnt(7)
	s_nop 1
	v_mov_b32_e32 v148, v222
	v_mov_b32_e32 v149, v223
	v_mov_b32_e32 v150, v224
	v_mov_b32_e32 v151, v225
	v_lshlrev_b32_e32 v152, 16, v148
	v_and_b32_e32 v153, 0xffff0000, v148
	v_lshlrev_b32_e32 v148, 16, v149
	v_and_b32_e32 v149, 0xffff0000, v149
	v_lshlrev_b32_e32 v168, 16, v150
	v_and_b32_e32 v169, 0xffff0000, v150
	v_lshlrev_b32_e32 v150, 16, v151
	v_and_b32_e32 v151, 0xffff0000, v151
	v_pk_fma_f32 v[154:155], v[130:131], v[146:147], v[148:149]
	v_pk_fma_f32 v[152:153], v[128:129], v[144:145], v[152:153]
	v_pk_fma_f32 v[150:151], v[126:127], v[142:143], v[150:151]
	v_pk_fma_f32 v[148:149], v[124:125], v[140:141], v[168:169]
	s_cbranch_vccnz .LBB0_1660
	s_mov_b64 s[40:41], 0
	global_store_dwordx4 v[184:185], v[152:155], off
	global_store_dwordx4 v[184:185], v[148:151], off offset:16
